# nt on the read-once activation loads of the elementwise phases 2, 5, 13 (on top of nt row-norm loads)
# baseline (speedup 1.0000x reference)
; DI u32x4 pack8(const float* f) { u32x4 w; w.x = pack2(f[0], f[1]); w.y = pack2(f[2], f[3]); w.z = pack2(f[4], f[5]); w.w = pack2(f[6], f[7]); return w; }
; DI float sigmoidf_(float x) { return __builtin_amdgcn_rcpf(1.0f + __expf(-x)); }
; DI void phase_rw_shift(const Ctx& c) {
;     ...
;   for (int u = gtid; u < (NTOK / 4) * 224; u += gstride) {
;     const int tq = u / 224, cv = u - tq * 224, col = cv * 8, tok0 = tq * 4, s0 = tok0 & (SEQ - 1);
;     const bf16_t* rp = raw + (size_t)tok0 * 1792 + col;
;     u32x4 R[6];
; #pragma unroll
;     for (int j = 0; j < 6; ++j) { const int sj = s0 - 1 + j; R[j] = (sj >= 0 && sj < SEQ) ? ld8(rp + (j - 1) * 1792) : (u32x4){0u, 0u, 0u, 0u}; }
;     float m0[8], m1[8];
; #pragma unroll
;     for (int j = 0; j < 8; ++j) { m0[j] = mu[col + j]; m1[j] = mu[1792 + col + j]; }
; #pragma unroll
;     for (int i = 0; i < 4; ++i) {
;       float prv[8], cur[8], nxt[8], o[8];
;       unpack8(R[i], prv); unpack8(R[i + 1], cur); unpack8(R[i + 2], nxt);
; #pragma unroll
;       for (int j = 0; j < 8; ++j) o[j] = cur[j] + m0[j] * (prv[j] - cur[j]) + m1[j] * (nxt[j] - cur[j]);
;       const size_t tok = (size_t)tok0 + i;
;       if (col < 1536) *(u32x4*)(rkv + tok * 1536 + col) = pack8(o);
;       else if (col < 1600) { for (int j = 0; j < 8; ++j) o[j] = tanhf(o[j]); *(u32x4*)(sm + tok * 256 + (col - 1536)) = pack8(o); }
;       else if (col < 1664) *(u32x4*)(sm + tok * 256 + 64 + (col - 1600)) = pack8(o);
;       else { for (int j = 0; j < 8; ++j) o[j] = sigmoidf_(o[j]); *(u32x4*)(sm + tok * 256 + 128 + (col - 1664)) = pack8(o); }
.LBB0_348:
	s_mov_b32 s2, 0x92492493
	v_mul_hi_i32 v0, v44, s2
	v_add_u32_e32 v0, v0, v44
	v_lshrrev_b32_e32 v1, 31, v0
	v_ashrrev_i32_e32 v0, 7, v0
	v_add_u32_e32 v6, v0, v1
	s_movk_i32 s2, 0xf900
	v_mad_u64_u32 v[48:49], s[2:3], v6, s2, v[40:41]
	v_lshlrev_b32_e32 v46, 2, v6
	s_movk_i32 s2, 0xe00
	v_and_b32_e32 v1, 0x7fc, v46
	v_mad_i64_i32 v[2:3], s[2:3], v46, s2, v[42:43]
	v_ashrrev_i32_e32 v49, 31, v48
	v_lshl_add_u64 v[4:5], v[48:49], 1, v[2:3]
	v_mov_b32_e32 v0, 0
	v_cmp_ne_u32_e32 vcc, 0, v1
	v_mov_b32_e32 v28, 0
	v_mov_b32_e32 v29, 0
	v_mov_b32_e32 v30, 0
	v_mov_b32_e32 v31, 0
	s_and_saveexec_b64 s[2:3], vcc
	s_cbranch_execz .LBB0_350
	v_add_co_u32_e32 v2, vcc, 0x77ff000, v4
	s_nop 1
	v_addc_co_u32_e32 v3, vcc, 0, v5, vcc
	global_load_dwordx4 v[28:31], v[2:3], off offset:512 nt
.LBB0_350:
	s_or_b64 exec, exec, s[2:3]
	v_add_co_u32_e32 v2, vcc, 0x7800000, v4
	s_movk_i32 s2, 0x7fc
	s_nop 0
	v_addc_co_u32_e32 v3, vcc, 0, v5, vcc
	global_load_dwordx4 v[36:39], v[2:3], off nt
	global_load_dwordx4 v[32:35], v[2:3], off offset:3584 nt
	v_add_co_u32_e32 v2, vcc, 0x7801000, v4
	s_nop 1
	v_addc_co_u32_e32 v3, vcc, 0, v5, vcc
	v_add_co_u32_e32 v8, vcc, 0x7802000, v4
	s_nop 1
	v_addc_co_u32_e32 v9, vcc, 0, v5, vcc
	global_load_dwordx4 v[24:27], v[2:3], off offset:3072 nt
	global_load_dwordx4 v[20:23], v[8:9], off offset:2560 nt
	v_cmp_ne_u32_e32 vcc, s2, v1
	v_mov_b32_e32 v1, 0
	v_mov_b32_e32 v2, 0
	v_mov_b32_e32 v3, 0
	s_and_saveexec_b64 s[2:3], vcc
	s_cbranch_execz .LBB0_352
	v_add_co_u32_e32 v0, vcc, 0x7803000, v4
	s_nop 1
	v_addc_co_u32_e32 v1, vcc, 0, v5, vcc
	global_load_dwordx4 v[0:3], v[0:1], off offset:2048 nt
.LBB0_352:
	s_or_b64 exec, exec, s[2:3]
	s_load_dwordx16 s[56:71], s[74:75], 0x40
	s_movk_i32 s2, 0xff20
	v_mad_u64_u32 v[50:51], s[2:3], v6, s2, v[44:45]
	s_mov_b64 s[2:3], 0x1c00
	s_waitcnt lgkmcnt(0)
	v_lshl_add_u64 v[8:9], v[48:49], 2, s[56:57]
	v_lshl_add_u64 v[10:11], v[8:9], 0, s[2:3]
	s_movk_i32 s2, 0x1000
	global_load_dwordx4 v[4:7], v[8:9], off offset:16 nt
	global_load_dwordx4 v[12:15], v[8:9], off nt
	v_add_co_u32_e32 v8, vcc, s2, v8
	s_movk_i32 s2, 0xbf
	s_nop 0
	v_addc_co_u32_e32 v9, vcc, 0, v9, vcc
	global_load_dwordx4 v[16:19], v[8:9], off offset:3072 nt
	s_nop 0
	global_load_dwordx4 v[8:11], v[10:11], off offset:16 nt
	s_movk_i32 s4, 0xc7
	s_movk_i32 s6, 0xcf
	s_waitcnt vmcnt(7)
	v_lshlrev_b32_e32 v54, 16, v36
	v_and_b32_e32 v55, 0xffff0000, v36
	v_lshlrev_b32_e32 v56, 16, v28
	v_and_b32_e32 v57, 0xffff0000, v28
	v_cmp_lt_i32_e64 s[2:3], s2, v50
	v_cmp_lt_u32_e64 s[4:5], s4, v50
	v_cmp_lt_u32_e32 vcc, s6, v50
	s_waitcnt vmcnt(6)
	v_lshlrev_b32_e32 v50, 16, v32
	v_and_b32_e32 v51, 0xffff0000, v32
	v_pk_add_f32 v[56:57], v[56:57], v[54:55] neg_lo:[0,1] neg_hi:[0,1]
	v_lshlrev_b32_e32 v36, 16, v37
	v_and_b32_e32 v37, 0xffff0000, v37
	v_lshlrev_b32_e32 v28, 16, v29
	v_and_b32_e32 v29, 0xffff0000, v29
	v_pk_add_f32 v[58:59], v[50:51], v[54:55] neg_lo:[0,1] neg_hi:[0,1]
	v_lshlrev_b32_e32 v32, 16, v33
	v_and_b32_e32 v33, 0xffff0000, v33
	v_pk_add_f32 v[28:29], v[28:29], v[36:37] neg_lo:[0,1] neg_hi:[0,1]
	v_lshlrev_b64 v[52:53], 1, v[48:49]
	v_ashrrev_i32_e32 v47, 31, v46
	v_lshl_add_u64 v[48:49], s[10:11], 0, v[52:53]
	s_waitcnt vmcnt(2)
	v_pk_fma_f32 v[56:57], v[56:57], v[12:13], v[54:55]
	v_pk_fma_f32 v[28:29], v[28:29], v[14:15], v[36:37]
	s_waitcnt vmcnt(1)
	v_pk_fma_f32 v[60:61], v[58:59], v[16:17], v[56:57]
	v_pk_add_f32 v[56:57], v[32:33], v[36:37] neg_lo:[0,1] neg_hi:[0,1]
	v_lshlrev_b32_e32 v58, 16, v30
	v_pk_fma_f32 v[62:63], v[56:57], v[18:19], v[28:29]
	v_lshlrev_b32_e32 v56, 16, v38
	v_and_b32_e32 v57, 0xffff0000, v38
	v_and_b32_e32 v59, 0xffff0000, v30
	v_lshlrev_b32_e32 v28, 16, v34
	v_and_b32_e32 v29, 0xffff0000, v34
	v_pk_add_f32 v[58:59], v[58:59], v[56:57] neg_lo:[0,1] neg_hi:[0,1]
	v_pk_add_f32 v[64:65], v[28:29], v[56:57] neg_lo:[0,1] neg_hi:[0,1]
	v_pk_fma_f32 v[58:59], v[58:59], v[4:5], v[56:57]
	v_lshlrev_b32_e32 v30, 16, v31
	s_waitcnt vmcnt(0)
	v_pk_fma_f32 v[64:65], v[64:65], v[8:9], v[58:59]
	v_lshlrev_b32_e32 v58, 16, v39
	v_and_b32_e32 v59, 0xffff0000, v39
	v_and_b32_e32 v31, 0xffff0000, v31
	v_lshlrev_b32_e32 v34, 16, v35
	v_and_b32_e32 v35, 0xffff0000, v35
	v_pk_add_f32 v[30:31], v[30:31], v[58:59] neg_lo:[0,1] neg_hi:[0,1]
	v_pk_add_f32 v[38:39], v[34:35], v[58:59] neg_lo:[0,1] neg_hi:[0,1]
	v_pk_fma_f32 v[30:31], v[30:31], v[6:7], v[58:59]
	s_nop 0
	v_pk_fma_f32 v[38:39], v[38:39], v[10:11], v[30:31]
	s_and_saveexec_b64 s[6:7], s[2:3]
	s_xor_b64 s[14:15], exec, s[6:7]
	s_cbranch_execz .LBB0_394
	s_and_saveexec_b64 s[6:7], s[4:5]
	s_xor_b64 s[6:7], exec, s[6:7]
	s_cbranch_execz .LBB0_359
	s_and_saveexec_b64 s[16:17], vcc
	s_xor_b64 s[16:17], exec, s[16:17]
	s_cbranch_execz .LBB0_356
	v_mul_f32_e32 v30, 0xbfb8aa3b, v60
	v_mul_f32_e32 v60, 0xbfb8aa3b, v62
	v_mul_f32_e32 v31, 0xbfb8aa3b, v61
	v_exp_f32_e32 v60, v60
	v_mul_f32_e32 v61, 0xbfb8aa3b, v63
	v_exp_f32_e32 v61, v61
	v_exp_f32_e32 v30, v30
	v_add_f32_e32 v60, 1.0, v60
	v_rcp_f32_e32 v62, v60
	v_add_f32_e32 v60, 1.0, v61
	v_mul_f32_e32 v61, 0xbfb8aa3b, v64
	v_exp_f32_e32 v31, v31
	v_exp_f32_e32 v61, v61
	v_mul_f32_e32 v63, 0xbfb8aa3b, v65
	v_mul_f32_e32 v38, 0xbfb8aa3b, v38
	v_mul_f32_e32 v39, 0xbfb8aa3b, v39
	v_exp_f32_e32 v63, v63
	v_exp_f32_e32 v38, v38
	v_exp_f32_e32 v39, v39
	v_add_f32_e32 v30, 1.0, v30
	v_add_f32_e32 v31, 1.0, v31
	v_rcp_f32_e32 v64, v60
	v_add_f32_e32 v60, 1.0, v61
	v_rcp_f32_e32 v30, v30
	v_rcp_f32_e32 v31, v31
	v_rcp_f32_e32 v65, v60
	v_add_f32_e32 v60, 1.0, v63
	v_add_f32_e32 v38, 1.0, v38
	v_add_f32_e32 v39, 1.0, v39
	v_rcp_f32_e32 v63, v60
	v_rcp_f32_e32 v38, v38
	v_rcp_f32_e32 v39, v39
	v_cvt_pk_bf16_f32 v60, v30, v31
	v_lshlrev_b64 v[30:31], 9, v[46:47]
	v_cvt_pk_bf16_f32 v61, v62, v64
	v_cvt_pk_bf16_f32 v62, v65, v63
	v_cvt_pk_bf16_f32 v63, v38, v39
	v_lshl_add_u64 v[30:31], v[48:49], 0, v[30:31]
	global_store_dwordx4 v[30:31], v[60:63], off offset:-3072

; DI u32x4 pack8(const float* f) { u32x4 w; w.x = pack2(f[0], f[1]); w.y = pack2(f[2], f[3]); w.z = pack2(f[4], f[5]); w.w = pack2(f[6], f[7]); return w; }
; DI float siluf_(float x) { return x * __builtin_amdgcn_rcpf(1.0f + __expf(-x)); }
; DI void phase_rw_shift(const Ctx& c) {
;     ...
;   for (int u = gtid; u < (NTOK / 4) * 64; u += gstride) {
;     const int tq = u >> 6, cv = u & 63, xc = 1024 + cv * 8, tok0 = tq * 4, s0 = tok0 & (SEQ - 1);
;     const bf16_t* rp = mraw + (size_t)tok0 * 2592 + 1024 + xc;
;     u32x4 R[6];
; #pragma unroll
;     for (int j = 0; j < 6; ++j) { const int sj = s0 - 1 + j; R[j] = (sj >= 0 && sj < SEQ) ? ld8(rp + (j - 1) * 2592) : (u32x4){0u, 0u, 0u, 0u}; }
;     float w0[8], w1[8], w2[8], bb[8];
; #pragma unroll
;     for (int j = 0; j < 8; ++j) { w0[j] = cw[xc + j]; w1[j] = cw[1536 + xc + j]; w2[j] = cw[3072 + xc + j]; bb[j] = cb[xc + j]; }
; #pragma unroll
;     for (int i = 0; i < 4; ++i) {
;       float prv[8], cur[8], nxt[8], o[8];
;       unpack8(R[i], prv); unpack8(R[i + 1], cur); unpack8(R[i + 2], nxt);
; #pragma unroll
;       for (int j = 0; j < 8; ++j) o[j] = siluf_(bb[j] + w0[j] * prv[j] + w1[j] * cur[j] + w2[j] * nxt[j]);
;       *(u32x4*)(BC + ((size_t)tok0 + i) * 512 + cv * 8) = pack8(o);
;     }
.LBB0_530:
	s_or_b64 exec, exec, s[10:11]
	v_lshlrev_b32_e32 v4, 2, v6
	v_mov_b32_e32 v5, v59
	v_lshl_add_u64 v[12:13], s[40:41], 0, v[4:5]
	v_add_co_u32_e32 v10, vcc, s13, v12
	v_lshl_add_u64 v[8:9], v[12:13], 0, s[6:7]
	s_nop 0
	v_addc_co_u32_e32 v11, vcc, 0, v13, vcc
	v_lshl_add_u64 v[14:15], v[12:13], 0, s[8:9]
	v_add_co_u32_e32 v12, vcc, s14, v12
	v_lshl_or_b32 v36, v6, 2, v79
	s_nop 0
	v_addc_co_u32_e32 v13, vcc, 0, v13, vcc
	global_load_dwordx4 v[4:7], v36, s[40:41] offset:16
	global_load_dwordx4 v[20:23], v36, s[40:41]
	global_load_dwordx4 v[24:27], v[10:11], off offset:2048 nt
	s_nop 0
	global_load_dwordx4 v[8:11], v[8:9], off offset:16 nt
	s_nop 0
	global_load_dwordx4 v[28:31], v[12:13], off nt
	s_nop 0
	global_load_dwordx4 v[12:15], v[14:15], off offset:16 nt
	s_nop 0
	global_load_dwordx4 v[16:19], v36, s[42:43] offset:16
	s_nop 0
	global_load_dwordx4 v[36:39], v36, s[42:43]
	s_waitcnt vmcnt(12)
	v_lshlrev_b32_e32 v68, 16, v44
	v_and_b32_e32 v69, 0xffff0000, v44
	s_waitcnt vmcnt(11)
	v_lshlrev_b32_e32 v66, 16, v52
	v_and_b32_e32 v67, 0xffff0000, v52
	s_waitcnt vmcnt(10)
	v_lshlrev_b32_e32 v62, 16, v48
	v_and_b32_e32 v63, 0xffff0000, v48
	v_lshlrev_b32_e32 v48, 16, v49
	v_and_b32_e32 v49, 0xffff0000, v49
	v_lshlrev_b32_e32 v74, 16, v46
	v_and_b32_e32 v75, 0xffff0000, v46
	v_lshlrev_b32_e32 v72, 16, v54
	v_and_b32_e32 v73, 0xffff0000, v54
	v_ashrrev_i32_e32 v61, 31, v60
	v_lshl_add_u64 v[64:65], s[2:3], 0, v[58:59]
	v_add_u32_e32 v77, s22, v77
	v_cmp_lt_i32_e32 vcc, s15, v77
	v_add_u32_e32 v78, s12, v78
	s_or_b64 s[4:5], vcc, s[4:5]
	s_waitcnt vmcnt(1)
	v_pk_fma_f32 v[74:75], v[4:5], v[74:75], v[16:17]
	s_waitcnt vmcnt(0)
	v_pk_fma_f32 v[68:69], v[20:21], v[68:69], v[36:37]
	v_pk_fma_f32 v[74:75], v[8:9], v[72:73], v[74:75]
	v_pk_fma_f32 v[68:69], v[24:25], v[66:67], v[68:69]
	s_nop 0
	v_pk_fma_f32 v[68:69], v[28:29], v[62:63], v[68:69]
	s_nop 0
	v_mul_f32_e32 v44, 0xbfb8aa3b, v68
	v_exp_f32_e32 v44, v44
	s_nop 0
	v_add_f32_e32 v44, 1.0, v44
	v_rcp_f32_e32 v70, v44
	v_mul_f32_e32 v44, 0xbfb8aa3b, v69
	v_exp_f32_e32 v44, v44
	s_nop 0
	v_add_f32_e32 v44, 1.0, v44
	v_rcp_f32_e32 v71, v44
	v_lshlrev_b32_e32 v44, 16, v45
	v_and_b32_e32 v45, 0xffff0000, v45
	v_pk_fma_f32 v[44:45], v[22:23], v[44:45], v[38:39]
	v_pk_mul_f32 v[70:71], v[68:69], v[70:71]
	v_lshlrev_b32_e32 v68, 16, v53
	v_and_b32_e32 v69, 0xffff0000, v53
	v_pk_fma_f32 v[44:45], v[26:27], v[68:69], v[44:45]
	s_nop 0
	v_pk_fma_f32 v[44:45], v[30:31], v[48:49], v[44:45]
	s_nop 0
	v_mul_f32_e32 v52, 0xbfb8aa3b, v44
	v_mul_f32_e32 v53, 0xbfb8aa3b, v45
	v_exp_f32_e32 v52, v52
	v_exp_f32_e32 v53, v53
	v_add_f32_e32 v52, 1.0, v52
	v_add_f32_e32 v53, 1.0, v53
	v_rcp_f32_e32 v52, v52
	v_rcp_f32_e32 v53, v53
	s_nop 0
	v_pk_mul_f32 v[44:45], v[44:45], v[52:53]
	v_lshlrev_b32_e32 v52, 16, v50
	v_and_b32_e32 v53, 0xffff0000, v50
	v_pk_fma_f32 v[74:75], v[12:13], v[52:53], v[74:75]
	s_nop 0
	v_mul_f32_e32 v46, 0xbfb8aa3b, v74
	v_exp_f32_e32 v46, v46
	s_nop 0
	v_add_f32_e32 v46, 1.0, v46
	v_rcp_f32_e32 v80, v46
	v_mul_f32_e32 v46, 0xbfb8aa3b, v75
	v_exp_f32_e32 v46, v46
	s_nop 0
	v_add_f32_e32 v46, 1.0, v46
	v_rcp_f32_e32 v81, v46
	v_lshlrev_b32_e32 v46, 16, v51
	v_pk_mul_f32 v[82:83], v[74:75], v[80:81]
	v_lshlrev_b32_e32 v80, 16, v47
	v_and_b32_e32 v81, 0xffff0000, v47
	v_lshlrev_b32_e32 v74, 16, v55
	v_and_b32_e32 v75, 0xffff0000, v55
	v_and_b32_e32 v47, 0xffff0000, v51
	v_pk_fma_f32 v[50:51], v[6:7], v[80:81], v[18:19]
	v_cvt_pk_bf16_f32 v82, v82, v83
	v_pk_fma_f32 v[50:51], v[10:11], v[74:75], v[50:51]
	v_cvt_pk_bf16_f32 v81, v44, v45
	v_pk_fma_f32 v[50:51], v[14:15], v[46:47], v[50:51]
	v_lshlrev_b64 v[44:45], 10, v[60:61]
	v_mul_f32_e32 v54, 0xbfb8aa3b, v50
	v_mul_f32_e32 v55, 0xbfb8aa3b, v51
	v_exp_f32_e32 v54, v54
	v_exp_f32_e32 v55, v55
	v_lshlrev_b32_e32 v60, 16, v40
	v_and_b32_e32 v61, 0xffff0000, v40
	v_add_f32_e32 v54, 1.0, v54
	v_add_f32_e32 v55, 1.0, v55
	v_rcp_f32_e32 v54, v54
	v_rcp_f32_e32 v55, v55
	v_lshl_add_u64 v[44:45], v[64:65], 0, v[44:45]
	v_cvt_pk_bf16_f32 v80, v70, v71
	v_pk_mul_f32 v[50:51], v[50:51], v[54:55]
	s_nop 0
	v_cvt_pk_bf16_f32 v83, v50, v51
	v_pk_fma_f32 v[50:51], v[20:21], v[66:67], v[36:37]
	global_store_dwordx4 v[44:45], v[80:83], off
	v_pk_fma_f32 v[50:51], v[24:25], v[62:63], v[50:51]
	v_pk_fma_f32 v[62:63], v[20:21], v[62:63], v[36:37]
	v_pk_fma_f32 v[50:51], v[28:29], v[60:61], v[50:51]
	v_pk_fma_f32 v[62:63], v[24:25], v[60:61], v[62:63]
	v_mul_f32_e32 v40, 0xbfb8aa3b, v50
	v_exp_f32_e32 v40, v40
	v_pk_fma_f32 v[20:21], v[20:21], v[60:61], v[36:37]
	v_add_f32_e32 v40, 1.0, v40
	v_rcp_f32_e32 v54, v40
	v_mul_f32_e32 v40, 0xbfb8aa3b, v51
	v_exp_f32_e32 v40, v40
	s_nop 0
	v_add_f32_e32 v40, 1.0, v40
	v_rcp_f32_e32 v55, v40
	s_nop 0
	v_pk_mul_f32 v[64:65], v[50:51], v[54:55]
	v_lshlrev_b32_e32 v54, 16, v41
	v_and_b32_e32 v55, 0xffff0000, v41
	v_pk_fma_f32 v[40:41], v[22:23], v[68:69], v[38:39]
	v_cvt_pk_bf16_f32 v64, v64, v65
	v_pk_fma_f32 v[40:41], v[26:27], v[48:49], v[40:41]
	s_nop 0
	v_pk_fma_f32 v[40:41], v[30:31], v[54:55], v[40:41]
	s_nop 0
	v_mul_f32_e32 v50, 0xbfb8aa3b, v40
	v_mul_f32_e32 v51, 0xbfb8aa3b, v41
	v_exp_f32_e32 v50, v50
	v_exp_f32_e32 v51, v51
	v_add_f32_e32 v50, 1.0, v50
	v_add_f32_e32 v51, 1.0, v51
	v_rcp_f32_e32 v50, v50
	v_rcp_f32_e32 v51, v51
	s_nop 0
	v_pk_mul_f32 v[66:67], v[40:41], v[50:51]
	v_pk_fma_f32 v[40:41], v[4:5], v[72:73], v[16:17]
	v_lshlrev_b32_e32 v50, 16, v42
	v_and_b32_e32 v51, 0xffff0000, v42
	v_pk_fma_f32 v[40:41], v[8:9], v[52:53], v[40:41]
	v_cvt_pk_bf16_f32 v65, v66, v67
	v_pk_fma_f32 v[40:41], v[12:13], v[50:51], v[40:41]
	s_nop 0
	v_mul_f32_e32 v42, 0xbfb8aa3b, v40
	v_exp_f32_e32 v42, v42
; DI u32x4 pack8(const float* f) { u32x4 w; w.x = pack2(f[0], f[1]); w.y = pack2(f[2], f[3]); w.z = pack2(f[4], f[5]); w.w = pack2(f[6], f[7]); return w; }
; DI float siluf_(float x) { return x * __builtin_amdgcn_rcpf(1.0f + __expf(-x)); }
; DI void phase_rw_shift(const Ctx& c) {
;     ...
;     const int tq = u >> 6, cv = u & 63, xc = 1024 + cv * 8, tok0 = tq * 4, s0 = tok0 & (SEQ - 1);
;     const bf16_t* rp = mraw + (size_t)tok0 * 2592 + 1024 + xc;
;     u32x4 R[6];
; #pragma unroll
;     for (int j = 0; j < 6; ++j) { const int sj = s0 - 1 + j; R[j] = (sj >= 0 && sj < SEQ) ? ld8(rp + (j - 1) * 2592) : (u32x4){0u, 0u, 0u, 0u}; }
;     float w0[8], w1[8], w2[8], bb[8];
; #pragma unroll
;     for (int j = 0; j < 8; ++j) { w0[j] = cw[xc + j]; w1[j] = cw[1536 + xc + j]; w2[j] = cw[3072 + xc + j]; bb[j] = cb[xc + j]; }
; #pragma unroll
;     for (int i = 0; i < 4; ++i) {
;       float prv[8], cur[8], nxt[8], o[8];
;       unpack8(R[i], prv); unpack8(R[i + 1], cur); unpack8(R[i + 2], nxt);
; #pragma unroll
;       for (int j = 0; j < 8; ++j) o[j] = siluf_(bb[j] + w0[j] * prv[j] + w1[j] * cur[j] + w2[j] * nxt[j]);
;       *(u32x4*)(BC + ((size_t)tok0 + i) * 512 + cv * 8) = pack8(o);
	s_nop 0
	v_add_f32_e32 v42, 1.0, v42
	v_rcp_f32_e32 v68, v42
	v_mul_f32_e32 v42, 0xbfb8aa3b, v41
	v_exp_f32_e32 v42, v42
	s_nop 0
	v_add_f32_e32 v42, 1.0, v42
	v_rcp_f32_e32 v69, v42
	s_nop 0
	v_pk_mul_f32 v[68:69], v[40:41], v[68:69]
	v_lshlrev_b32_e32 v40, 16, v43
	v_and_b32_e32 v41, 0xffff0000, v43
	v_pk_fma_f32 v[42:43], v[6:7], v[74:75], v[18:19]
	v_cvt_pk_bf16_f32 v66, v68, v69
	v_pk_fma_f32 v[42:43], v[10:11], v[46:47], v[42:43]
	v_lshlrev_b32_e32 v68, 16, v35
	v_pk_fma_f32 v[42:43], v[14:15], v[40:41], v[42:43]
	v_and_b32_e32 v69, 0xffff0000, v35
	v_mul_f32_e32 v58, 0xbfb8aa3b, v42
	v_exp_f32_e32 v58, v58
	s_nop 0
	v_add_f32_e32 v58, 1.0, v58
	v_rcp_f32_e32 v70, v58
	v_mul_f32_e32 v58, 0xbfb8aa3b, v43
	v_exp_f32_e32 v58, v58
	s_nop 0
	v_add_f32_e32 v58, 1.0, v58
	v_rcp_f32_e32 v71, v58
	s_nop 0
	v_pk_mul_f32 v[42:43], v[42:43], v[70:71]
	s_nop 0
	v_cvt_pk_bf16_f32 v67, v42, v43
	v_lshlrev_b32_e32 v42, 16, v32
	v_and_b32_e32 v43, 0xffff0000, v32
	v_pk_fma_f32 v[62:63], v[28:29], v[42:43], v[62:63]
	global_store_dwordx4 v[44:45], v[64:67], off offset:1024
	v_mul_f32_e32 v32, 0xbfb8aa3b, v62
	v_exp_f32_e32 v32, v32
	v_lshlrev_b32_e32 v66, 16, v34
	v_and_b32_e32 v67, 0xffff0000, v34
	v_pk_fma_f32 v[20:21], v[24:25], v[42:43], v[20:21]
	v_add_f32_e32 v32, 1.0, v32
	v_rcp_f32_e32 v64, v32
	v_mul_f32_e32 v32, 0xbfb8aa3b, v63
	v_exp_f32_e32 v32, v32
	s_nop 0
	v_add_f32_e32 v32, 1.0, v32
	v_rcp_f32_e32 v65, v32
	s_nop 0
	v_pk_mul_f32 v[62:63], v[62:63], v[64:65]
	v_lshlrev_b32_e32 v64, 16, v33
	v_and_b32_e32 v65, 0xffff0000, v33
	v_pk_fma_f32 v[32:33], v[22:23], v[48:49], v[38:39]
	v_pk_fma_f32 v[22:23], v[22:23], v[54:55], v[38:39]
	v_pk_fma_f32 v[32:33], v[26:27], v[54:55], v[32:33]
	v_pk_fma_f32 v[22:23], v[26:27], v[64:65], v[22:23]
	v_pk_fma_f32 v[32:33], v[30:31], v[64:65], v[32:33]
	s_nop 0
	v_mul_f32_e32 v48, 0xbfb8aa3b, v32
	v_mul_f32_e32 v49, 0xbfb8aa3b, v33
	v_exp_f32_e32 v48, v48
	v_exp_f32_e32 v49, v49
	v_add_f32_e32 v48, 1.0, v48
	v_add_f32_e32 v49, 1.0, v49
	v_rcp_f32_e32 v48, v48
	v_rcp_f32_e32 v49, v49
	s_nop 0
	v_pk_mul_f32 v[48:49], v[32:33], v[48:49]
	v_pk_fma_f32 v[32:33], v[4:5], v[52:53], v[16:17]
	v_pk_fma_f32 v[4:5], v[4:5], v[50:51], v[16:17]
	v_pk_fma_f32 v[32:33], v[8:9], v[50:51], v[32:33]
	v_pk_fma_f32 v[4:5], v[8:9], v[66:67], v[4:5]
	v_pk_fma_f32 v[32:33], v[12:13], v[66:67], v[32:33]
	s_nop 0
	v_mul_f32_e32 v34, 0xbfb8aa3b, v32
	v_exp_f32_e32 v34, v34
	s_nop 0
	v_add_f32_e32 v34, 1.0, v34
	v_rcp_f32_e32 v52, v34
	v_mul_f32_e32 v34, 0xbfb8aa3b, v33
	v_exp_f32_e32 v34, v34
	s_nop 0
	v_add_f32_e32 v34, 1.0, v34
	v_rcp_f32_e32 v53, v34
	s_nop 0
	v_pk_mul_f32 v[52:53], v[32:33], v[52:53]
	v_pk_fma_f32 v[32:33], v[6:7], v[46:47], v[18:19]
	s_nop 0
	v_pk_fma_f32 v[32:33], v[10:11], v[40:41], v[32:33]
	s_nop 0
	v_pk_fma_f32 v[32:33], v[14:15], v[68:69], v[32:33]
	s_nop 0
	v_mul_f32_e32 v34, 0xbfb8aa3b, v32
	v_mul_f32_e32 v35, 0xbfb8aa3b, v33
	v_exp_f32_e32 v34, v34
	v_exp_f32_e32 v35, v35
	v_add_f32_e32 v34, 1.0, v34
	v_add_f32_e32 v35, 1.0, v35
	v_rcp_f32_e32 v34, v34
	v_rcp_f32_e32 v35, v35
	s_nop 0
	v_pk_mul_f32 v[46:47], v[32:33], v[34:35]
	v_cvt_pk_bf16_f32 v32, v62, v63
	v_cvt_pk_bf16_f32 v33, v48, v49
	v_cvt_pk_bf16_f32 v34, v52, v53
	v_cvt_pk_bf16_f32 v35, v46, v47
	global_store_dwordx4 v[44:45], v[32:35], off offset:2048
	s_nop 1
	v_lshlrev_b32_e32 v32, 16, v0
	v_and_b32_e32 v33, 0xffff0000, v0
	v_pk_fma_f32 v[20:21], v[28:29], v[32:33], v[20:21]
	s_nop 0
	v_mul_f32_e32 v0, 0xbfb8aa3b, v20
	v_exp_f32_e32 v0, v0
	s_nop 0
	v_add_f32_e32 v0, 1.0, v0
	v_rcp_f32_e32 v24, v0
	v_mul_f32_e32 v0, 0xbfb8aa3b, v21
	v_exp_f32_e32 v0, v0
	s_nop 0
	v_add_f32_e32 v0, 1.0, v0
	v_rcp_f32_e32 v25, v0
	v_lshlrev_b32_e32 v0, 16, v1
	v_and_b32_e32 v1, 0xffff0000, v1
	v_pk_fma_f32 v[0:1], v[30:31], v[0:1], v[22:23]
	v_pk_mul_f32 v[20:21], v[20:21], v[24:25]
	v_mul_f32_e32 v22, 0xbfb8aa3b, v0
	v_mul_f32_e32 v23, 0xbfb8aa3b, v1
	v_exp_f32_e32 v22, v22
	v_exp_f32_e32 v23, v23
	v_add_f32_e32 v22, 1.0, v22
	v_add_f32_e32 v23, 1.0, v23
	v_rcp_f32_e32 v22, v22
	v_rcp_f32_e32 v23, v23
	s_nop 0
	v_pk_mul_f32 v[22:23], v[0:1], v[22:23]
	v_lshlrev_b32_e32 v0, 16, v2
	v_and_b32_e32 v1, 0xffff0000, v2
	v_pk_fma_f32 v[0:1], v[12:13], v[0:1], v[4:5]
	s_nop 0
	v_mul_f32_e32 v2, 0xbfb8aa3b, v0
	v_exp_f32_e32 v2, v2
	s_nop 0
	v_add_f32_e32 v2, 1.0, v2
	v_rcp_f32_e32 v4, v2
	v_mul_f32_e32 v2, 0xbfb8aa3b, v1
	v_exp_f32_e32 v2, v2
	s_nop 0
	v_add_f32_e32 v2, 1.0, v2
	v_rcp_f32_e32 v5, v2
	s_nop 0
	v_pk_mul_f32 v[4:5], v[0:1], v[4:5]
	v_lshlrev_b32_e32 v0, 16, v3
	v_and_b32_e32 v1, 0xffff0000, v3
	v_pk_fma_f32 v[2:3], v[6:7], v[40:41], v[18:19]
	s_nop 0
	v_pk_fma_f32 v[2:3], v[10:11], v[68:69], v[2:3]
	s_nop 0
	v_pk_fma_f32 v[0:1], v[14:15], v[0:1], v[2:3]
	s_nop 0
	v_mul_f32_e32 v2, 0xbfb8aa3b, v0
	v_mul_f32_e32 v3, 0xbfb8aa3b, v1
	v_exp_f32_e32 v2, v2
	v_exp_f32_e32 v3, v3
	v_add_f32_e32 v2, 1.0, v2
	v_add_f32_e32 v3, 1.0, v3
	v_rcp_f32_e32 v2, v2
	v_rcp_f32_e32 v3, v3
	s_nop 0
	v_pk_mul_f32 v[6:7], v[0:1], v[2:3]
	v_cvt_pk_bf16_f32 v0, v20, v21
	v_cvt_pk_bf16_f32 v1, v22, v23
	v_cvt_pk_bf16_f32 v2, v4, v5
	v_cvt_pk_bf16_f32 v3, v6, v7
	global_store_dwordx4 v[44:45], v[0:3], off offset:3072
	s_andn2_b64 exec, exec, s[4:5]
	s_cbranch_execz .LBB0_535
.LBB0_531:
	v_ashrrev_i32_e32 v0, 4, v77
	v_and_b32_e32 v6, 0x1f8, v78
	v_and_b32_e32 v60, -4, v0
	s_movk_i32 s10, 0x1440
	v_mad_i64_i32 v[2:3], s[10:11], v60, s10, v[56:57]
	v_lshlrev_b32_e32 v58, 1, v6
	v_and_b32_e32 v0, 0x7fc, v0
	v_lshl_add_u64 v[2:3], v[2:3], 0, v[58:59]
	s_mov_b64 s[10:11], 0x800
	v_lshl_add_u64 v[4:5], v[2:3], 0, s[10:11]
	v_cmp_ne_u32_e32 vcc, 0, v0
	v_mov_b32_e32 v44, 0
	v_mov_b32_e32 v45, 0
	v_mov_b32_e32 v46, 0
	v_mov_b32_e32 v47, 0
	s_and_saveexec_b64 s[10:11], vcc
	s_cbranch_execz .LBB0_533
	v_add_co_u32_e32 v2, vcc, 0xe7ff000, v4
	s_nop 1
	v_addc_co_u32_e32 v3, vcc, 0, v5, vcc
	global_load_dwordx4 v[44:47], v[2:3], off offset:960 nt
.LBB0_533:
	s_or_b64 exec, exec, s[10:11]
	v_add_co_u32_e32 v2, vcc, 0xe800000, v4
	s_movk_i32 s10, 0x7fc
	s_nop 0
	v_addc_co_u32_e32 v3, vcc, 0, v5, vcc
	v_add_co_u32_e32 v8, vcc, 0xe801000, v4
	v_mov_b32_e32 v1, 0
	s_nop 0
	v_addc_co_u32_e32 v9, vcc, 0, v5, vcc
	global_load_dwordx4 v[52:55], v[2:3], off offset:2048 nt
	global_load_dwordx4 v[48:51], v[8:9], off offset:3136 nt
	v_add_co_u32_e32 v2, vcc, 0xe803000, v4
	s_nop 1
	v_addc_co_u32_e32 v3, vcc, 0, v5, vcc
	v_add_co_u32_e32 v8, vcc, 0xe804000, v4
	s_nop 1
	v_addc_co_u32_e32 v9, vcc, 0, v5, vcc
	global_load_dwordx4 v[40:43], v[2:3], off offset:128 nt
	global_load_dwordx4 v[32:35], v[8:9], off offset:1216 nt
	v_cmp_ne_u32_e32 vcc, s10, v0
	v_mov_b32_e32 v0, 0
	v_mov_b32_e32 v2, 0
	v_mov_b32_e32 v3, 0
	s_and_saveexec_b64 s[10:11], vcc
	s_cbranch_execz .LBB0_530
	v_add_co_u32_e32 v0, vcc, 0xe805000, v4
	s_nop 1
	v_addc_co_u32_e32 v1, vcc, 0, v5, vcc
	global_load_dwordx4 v[0:3], v[0:1], off offset:2304 nt
	s_branch .LBB0_530

; DI void phase_post0(const Ctx& c) {
;     ...
;     for (int tok0 = gw; tok0 < NTOK; tok0 += 2 * nw) {
;       const int c = lane * 8;
;       u32x4 Q[2][7];
; #pragma unroll
;       for (int i = 0; i < 2; ++i) { const int tok = tok0 + i * nw; if (tok < NTOK) {
;         Q[i][0] = ld8(E0 + (size_t)tok * 512 + c); Q[i][1] = ld8(E1 + (size_t)tok * 512 + c);
;         Q[i][2] = ld8(RKV + (size_t)tok * 1536 + c); Q[i][3] = ld8(RKV + (size_t)tok * 1536 + 512 + c); Q[i][4] = ld8(RKV + (size_t)tok * 1536 + 1024 + c);
;         Q[i][5] = ld8(Ab + (size_t)tok * 512 + c); Q[i][6] = ld8(G + (size_t)tok * 512 + c); } }
.LBB0_831:
	v_ashrrev_i32_e32 v93, 31, v92
	v_lshlrev_b64 v[56:57], 10, v[92:93]
	v_lshl_add_u64 v[94:95], v[82:83], 0, v[56:57]
	v_lshl_add_u64 v[52:53], v[84:85], 0, v[56:57]
	global_load_dwordx4 v[64:67], v[94:95], off nt
	global_load_dwordx4 v[60:63], v[52:53], off nt
	v_mad_i64_i32 v[52:53], s[2:3], v92, s7, v[90:91]
	v_lshl_add_u64 v[58:59], v[86:87], 0, v[56:57]
	v_lshl_add_u64 v[56:57], v[88:89], 0, v[56:57]
	global_load_dwordx4 v[76:79], v[52:53], off nt
	global_load_dwordx4 v[68:71], v[52:53], off offset:1024 nt
	s_nop 0
	global_load_dwordx4 v[52:55], v[52:53], off offset:2048 nt
	s_nop 0
	global_load_dwordx4 v[72:75], v[58:59], off nt
	v_add_u32_e32 v92, s15, v92
	global_load_dwordx4 v[56:59], v[56:57], off nt
	v_cmp_gt_i32_e32 vcc, s6, v92
	v_ashrrev_i32_e32 v93, 31, v92
	s_and_saveexec_b64 s[2:3], vcc
	s_cbranch_execz .LBB0_833
	v_lshlrev_b64 v[48:49], 10, v[92:93]
	v_lshl_add_u64 v[24:25], v[82:83], 0, v[48:49]
	v_lshl_add_u64 v[28:29], v[84:85], 0, v[48:49]
	v_mad_i64_i32 v[40:41], s[12:13], v92, s7, v[90:91]
	v_lshl_add_u64 v[44:45], v[86:87], 0, v[48:49]
	v_lshl_add_u64 v[48:49], v[88:89], 0, v[48:49]
	global_load_dwordx4 v[24:27], v[24:25], off nt
	s_nop 0
	global_load_dwordx4 v[28:31], v[28:29], off nt
	s_nop 0
	global_load_dwordx4 v[32:35], v[40:41], off nt
	global_load_dwordx4 v[36:39], v[40:41], off offset:1024 nt
	s_nop 0
	global_load_dwordx4 v[40:43], v[40:41], off offset:2048 nt
	s_nop 0
	global_load_dwordx4 v[44:47], v[44:45], off nt
	s_nop 0
	global_load_dwordx4 v[48:51], v[48:49], off nt

; DI float siluf_(float x) { return x * __builtin_amdgcn_rcpf(1.0f + __expf(-x)); }
; DI void phase_post0(const Ctx& c) {
;     ...
;     for (int u = gw; u < NTOK; u += nw) {
;       const int tp = u >> 1, gq = u & 1, col = gq * 512 + lane * 8, head = col >> 6, tok0 = tp * 2, t0 = tok0 & (SEQ - 1);
;       bf16_t* zp = raw + (size_t)tok0 * 2592 + col;
;       const bf16_t* rp = zp + 1024;
;       u32x4 R[4], Yq[2][2], Zq[2];
; #pragma unroll
;       for (int j = 0; j < 4; ++j) { const int tj = t0 - 1 + j; R[j] = (tj >= 0 && tj < SEQ) ? ld8(rp + (j - 1) * 2592) : (u32x4){0u, 0u, 0u, 0u}; }
; #pragma unroll
;       for (int i = 0; i < 2; ++i) { Yq[i][0] = ld8(Y0 + (size_t)(tok0 + i) * 1024 + col); Yq[i][1] = ld8(Y1 + (size_t)(tok0 + i) * 1024 + col); Zq[i] = ld8(zp + i * 2592); }
;       float w0[8], w1[8], w2[8], bb[8], nw_[8];
; #pragma unroll
;       for (int j = 0; j < 8; ++j) { w0[j] = cw[col + j]; w1[j] = cw[1536 + col + j]; w2[j] = cw[3072 + col + j]; bb[j] = cb[col + j]; nw_[j] = p.mb_norm_w[col + j]; }
;       const float D = p.mb_D[head];
; #pragma unroll
;       for (int i = 0; i < 2; ++i) {
;         float y0[8], y1[8], z[8], cur[8], prv[8], nxt[8], o[8];
;         unpack8(Yq[i][0], y0); unpack8(Yq[i][1], y1); unpack8(Zq[i], z); unpack8(R[i], prv); unpack8(R[i + 1], cur); unpack8(R[i + 2], nxt);
;         float ss = 0.f;
; #pragma unroll
;         for (int j = 0; j < 8; ++j) { const float xs = siluf_(bb[j] + w0[j] * prv[j] + w1[j] * cur[j] + w2[j] * nxt[j]);
;           const float yy = (y0[j] + y1[j] + D * xs) * siluf_(z[j]); o[j] = yy; ss += yy * yy; }
.LBB0_836:
	s_or_b64 exec, exec, s[12:13]
	v_ashrrev_i32_e32 v21, 31, v20
	v_lshl_add_u64 v[52:53], s[54:55], 0, v[74:75]
	v_lshl_add_u64 v[54:55], s[2:3], 0, v[74:75]
	v_lshlrev_b32_e32 v74, 2, v22
	v_lshlrev_b64 v[20:21], 11, v[20:21]
	v_lshl_add_u64 v[28:29], v[52:53], 0, v[20:21]
	v_lshl_add_u64 v[20:21], v[54:55], 0, v[20:21]
	v_lshl_add_u64 v[32:33], s[40:41], 0, v[74:75]
	global_load_dwordx4 v[60:63], v[78:79], off nt
	global_load_dwordx4 v[12:15], v74, s[40:41] offset:16
	global_load_dwordx4 v[16:19], v74, s[42:43] offset:16
	global_load_dwordx4 v[68:71], v[28:29], off nt
	global_load_dwordx4 v[64:67], v[20:21], off nt
	v_lshl_add_u64 v[20:21], v[32:33], 0, s[6:7]
	global_load_dwordx4 v[44:47], v[20:21], off offset:16 nt
	v_lshl_add_u64 v[20:21], v[32:33], 0, s[8:9]
	global_load_dwordx4 v[48:51], v[20:21], off offset:16 nt
	v_add_co_u32_e32 v82, vcc, s20, v78
	v_lshrrev_b32_e32 v20, 4, v22
	s_nop 0
	v_addc_co_u32_e32 v83, vcc, 0, v79, vcc
	v_and_b32_e32 v20, 60, v20
	s_waitcnt vmcnt(9)
	v_lshlrev_b32_e32 v100, 16, v4
	v_and_b32_e32 v101, 0xffff0000, v4
	v_add_co_u32_e32 v4, vcc, s20, v32
	global_load_dword v84, v20, s[48:49]
	v_lshlrev_b32_e32 v104, 16, v5
	v_and_b32_e32 v105, 0xffff0000, v5
	global_load_dwordx4 v[20:23], v74, s[40:41]
	global_load_dwordx4 v[28:31], v74, s[42:43]
	v_addc_co_u32_e32 v5, vcc, 0, v33, vcc
	v_lshlrev_b32_e32 v106, 16, v6
	v_and_b32_e32 v107, 0xffff0000, v6
	v_add_co_u32_e32 v6, vcc, s21, v32
	v_lshlrev_b32_e32 v90, 16, v7
	v_and_b32_e32 v91, 0xffff0000, v7
	v_addc_co_u32_e32 v7, vcc, 0, v33, vcc
	global_load_dwordx4 v[36:39], v[4:5], off offset:2048 nt
	global_load_dwordx4 v[40:43], v[6:7], off nt
	v_or_b32_e32 v56, 1, v102
	s_waitcnt vmcnt(13)
	v_lshlrev_b32_e32 v86, 16, v8
	v_and_b32_e32 v87, 0xffff0000, v8
	v_lshlrev_b32_e32 v88, 16, v9
	v_and_b32_e32 v89, 0xffff0000, v9
	v_lshlrev_b32_e32 v92, 16, v10
	v_and_b32_e32 v93, 0xffff0000, v10
	v_lshlrev_b32_e32 v94, 16, v11
	v_and_b32_e32 v95, 0xffff0000, v11
	v_ashrrev_i32_e32 v57, 31, v56
	global_load_dwordx4 v[32:35], v[82:83], off offset:1088 nt
	global_load_dwordx4 v[4:7], v74, s[50:51] offset:16
	global_load_dwordx4 v[8:11], v74, s[50:51]
	v_lshlrev_b64 v[56:57], 11, v[56:57]
	v_lshl_add_u64 v[52:53], v[52:53], 0, v[56:57]
	v_lshl_add_u64 v[54:55], v[54:55], 0, v[56:57]
	global_load_dwordx4 v[56:59], v[52:53], off nt
	s_nop 0
	global_load_dwordx4 v[52:55], v[54:55], off nt
	s_waitcnt vmcnt(17)
	v_lshlrev_b32_e32 v98, 16, v27
	v_and_b32_e32 v99, 0xffff0000, v27
	v_lshlrev_b32_e32 v96, 16, v26
	v_and_b32_e32 v97, 0xffff0000, v26
	v_add_u32_e32 v102, s15, v102
	v_add_u32_e32 v103, s16, v103
	s_waitcnt vmcnt(16)
	v_lshlrev_b32_e32 v108, 16, v63
	s_waitcnt vmcnt(14)
	v_pk_fma_f32 v[90:91], v[14:15], v[90:91], v[18:19]
	v_mul_f32_e32 v27, 0xbfb8aa3b, v108
	s_waitcnt vmcnt(13)
	v_lshlrev_b32_e32 v110, 16, v71
	s_waitcnt vmcnt(11)
	v_pk_fma_f32 v[90:91], v[46:47], v[94:95], v[90:91]
	v_and_b32_e32 v111, 0xffff0000, v71
	v_lshlrev_b32_e32 v114, 16, v70
	v_and_b32_e32 v115, 0xffff0000, v70
	s_waitcnt vmcnt(10)
	v_pk_fma_f32 v[70:71], v[50:51], v[98:99], v[90:91]
	v_exp_f32_e32 v27, v27
	v_lshlrev_b32_e32 v112, 16, v67
	v_and_b32_e32 v113, 0xffff0000, v67
	v_mul_f32_e32 v67, 0xbfb8aa3b, v70
	v_and_b32_e32 v109, 0xffff0000, v63
	v_exp_f32_e32 v67, v67
	v_mul_f32_e32 v63, 0xbfb8aa3b, v109
	v_exp_f32_e32 v63, v63
	v_mul_f32_e32 v74, 0xbfb8aa3b, v71
	v_add_f32_e32 v27, 1.0, v27
	v_exp_f32_e32 v74, v74
	v_rcp_f32_e32 v90, v27
	v_add_f32_e32 v27, 1.0, v67
	v_rcp_f32_e32 v116, v27
	v_pk_fma_f32 v[26:27], v[12:13], v[106:107], v[16:17]
	v_add_f32_e32 v63, 1.0, v63
	v_pk_fma_f32 v[26:27], v[44:45], v[92:93], v[26:27]
	v_rcp_f32_e32 v91, v63
	v_add_f32_e32 v63, 1.0, v74
	v_pk_fma_f32 v[26:27], v[48:49], v[96:97], v[26:27]
	v_rcp_f32_e32 v117, v63
	v_mul_f32_e32 v63, 0xbfb8aa3b, v26
	v_exp_f32_e32 v63, v63
	v_lshlrev_b32_e32 v118, 16, v66
	v_and_b32_e32 v119, 0xffff0000, v66
	v_lshlrev_b32_e32 v66, 16, v62
	v_and_b32_e32 v67, 0xffff0000, v62
	v_add_f32_e32 v62, 1.0, v63
	v_mul_f32_e32 v63, 0xbfb8aa3b, v66
	v_exp_f32_e32 v63, v63
	v_mul_f32_e32 v74, 0xbfb8aa3b, v27
	v_exp_f32_e32 v74, v74
	s_waitcnt vmcnt(7)
	v_pk_fma_f32 v[104:105], v[22:23], v[104:105], v[30:31]
	v_add_f32_e32 v106, 1.0, v63
	v_mul_f32_e32 v63, 0xbfb8aa3b, v67
	v_pk_mul_f32 v[90:91], v[90:91], v[108:109]
	v_exp_f32_e32 v107, v63
	v_lshlrev_b32_e32 v108, 16, v25
	v_and_b32_e32 v109, 0xffff0000, v25
	s_waitcnt vmcnt(6)
	v_pk_fma_f32 v[104:105], v[38:39], v[88:89], v[104:105]
	v_add_f32_e32 v63, 1.0, v74
	s_waitcnt vmcnt(5)
; DI float siluf_(float x) { return x * __builtin_amdgcn_rcpf(1.0f + __expf(-x)); }
; DI void phase_post0(const Ctx& c) {
;     ...
;       for (int i = 0; i < 2; ++i) {
;         float y0[8], y1[8], z[8], cur[8], prv[8], nxt[8], o[8];
;         unpack8(Yq[i][0], y0); unpack8(Yq[i][1], y1); unpack8(Zq[i], z); unpack8(R[i], prv); unpack8(R[i + 1], cur); unpack8(R[i + 2], nxt);
;         float ss = 0.f;
; #pragma unroll
;         for (int j = 0; j < 8; ++j) { const float xs = siluf_(bb[j] + w0[j] * prv[j] + w1[j] * cur[j] + w2[j] * nxt[j]);
;           const float yy = (y0[j] + y1[j] + D * xs) * siluf_(z[j]); o[j] = yy; ss += yy * yy; }
	v_pk_fma_f32 v[104:105], v[42:43], v[108:109], v[104:105]
	v_rcp_f32_e32 v62, v62
	v_mul_f32_e32 v25, 0xbfb8aa3b, v104
	v_exp_f32_e32 v25, v25
	v_rcp_f32_e32 v63, v63
	v_add_f32_e32 v74, 1.0, v107
	v_rcp_f32_e32 v106, v106
	v_rcp_f32_e32 v107, v74
	v_pk_add_f32 v[110:111], v[110:111], v[112:113]
	v_pk_mul_f32 v[70:71], v[70:71], v[116:117]
	v_add_f32_e32 v25, 1.0, v25
	v_pk_fma_f32 v[70:71], v[84:85], v[70:71], v[110:111] op_sel_hi:[0,1,1]
	v_pk_mul_f32 v[26:27], v[26:27], v[62:63]
	v_pk_add_f32 v[62:63], v[114:115], v[118:119]
	v_and_b32_e32 v111, 0xffff0000, v61
	v_rcp_f32_e32 v112, v25
	v_mul_f32_e32 v25, 0xbfb8aa3b, v105
	v_pk_fma_f32 v[26:27], v[26:27], v[84:85], v[62:63] op_sel_hi:[1,0,1]
	v_pk_mul_f32 v[62:63], v[106:107], v[66:67]
	v_lshlrev_b32_e32 v106, 16, v65
	v_and_b32_e32 v107, 0xffff0000, v65
	v_exp_f32_e32 v25, v25
	v_mul_f32_e32 v65, 0xbfb8aa3b, v111
	v_lshlrev_b32_e32 v110, 16, v61
	v_exp_f32_e32 v65, v65
	v_mul_f32_e32 v61, 0xbfb8aa3b, v110
	v_exp_f32_e32 v61, v61
	v_add_f32_e32 v25, 1.0, v25
	v_lshlrev_b32_e32 v66, 16, v69
	v_and_b32_e32 v67, 0xffff0000, v69
	v_rcp_f32_e32 v113, v25
	v_add_f32_e32 v25, 1.0, v65
	v_rcp_f32_e32 v115, v25
	v_pk_add_f32 v[66:67], v[66:67], v[106:107]
	v_lshlrev_b32_e32 v106, 16, v24
	v_and_b32_e32 v107, 0xffff0000, v24
	v_pk_fma_f32 v[24:25], v[20:21], v[100:101], v[28:29]
	v_add_f32_e32 v61, 1.0, v61
	v_pk_fma_f32 v[24:25], v[36:37], v[86:87], v[24:25]
	v_rcp_f32_e32 v114, v61
	v_pk_fma_f32 v[24:25], v[40:41], v[106:107], v[24:25]
	v_pk_mul_f32 v[104:105], v[104:105], v[112:113]
	v_mul_f32_e32 v61, 0xbfb8aa3b, v24
	v_exp_f32_e32 v61, v61
	v_pk_fma_f32 v[66:67], v[104:105], v[84:85], v[66:67] op_sel_hi:[1,0,1]
	v_pk_mul_f32 v[104:105], v[114:115], v[110:111]
	v_and_b32_e32 v69, 0xffff0000, v64
	v_pk_mul_f32 v[66:67], v[104:105], v[66:67]
	v_lshlrev_b32_e32 v104, 16, v68
	v_and_b32_e32 v105, 0xffff0000, v68
	v_lshlrev_b32_e32 v68, 16, v64
	v_lshlrev_b32_e32 v64, 16, v60
	v_and_b32_e32 v65, 0xffff0000, v60
	v_add_f32_e32 v60, 1.0, v61
	v_mul_f32_e32 v61, 0xbfb8aa3b, v64
	v_exp_f32_e32 v61, v61
	v_mul_f32_e32 v74, 0xbfb8aa3b, v25
	v_exp_f32_e32 v74, v74
	v_rcp_f32_e32 v60, v60
	v_add_f32_e32 v100, 1.0, v61
	v_mul_f32_e32 v61, 0xbfb8aa3b, v65
	v_exp_f32_e32 v101, v61
	v_add_f32_e32 v61, 1.0, v74
	v_rcp_f32_e32 v61, v61
	v_pk_fma_f32 v[14:15], v[14:15], v[94:95], v[18:19]
	v_add_f32_e32 v74, 1.0, v101
	v_pk_fma_f32 v[14:15], v[46:47], v[98:99], v[14:15]
	v_pk_mul_f32 v[24:25], v[24:25], v[60:61]
	v_pk_add_f32 v[60:61], v[104:105], v[68:69]
	v_lshlrev_b32_e32 v68, 16, v3
	v_and_b32_e32 v69, 0xffff0000, v3
	v_pk_fma_f32 v[14:15], v[50:51], v[68:69], v[14:15]
	v_rcp_f32_e32 v100, v100
	v_mul_f32_e32 v3, 0xbfb8aa3b, v14
	v_exp_f32_e32 v3, v3
	v_rcp_f32_e32 v101, v74
	s_waitcnt vmcnt(4)
	v_and_b32_e32 v19, 0xffff0000, v35
	v_mul_f32_e32 v47, 0xbfb8aa3b, v19
	v_add_f32_e32 v3, 1.0, v3
	v_rcp_f32_e32 v46, v3
	v_mul_f32_e32 v3, 0xbfb8aa3b, v15
	v_exp_f32_e32 v3, v3
	v_exp_f32_e32 v51, v47
	v_pk_fma_f32 v[24:25], v[24:25], v[84:85], v[60:61] op_sel_hi:[1,0,1]
	v_pk_mul_f32 v[60:61], v[100:101], v[64:65]
	v_add_f32_e32 v3, 1.0, v3
	v_rcp_f32_e32 v47, v3
	v_pk_mul_f32 v[24:25], v[60:61], v[24:25]
	s_waitcnt vmcnt(1)
	v_lshlrev_b32_e32 v60, 16, v59
	v_and_b32_e32 v61, 0xffff0000, v59
	s_waitcnt vmcnt(0)
	v_lshlrev_b32_e32 v64, 16, v55
	v_and_b32_e32 v65, 0xffff0000, v55
	v_add_f32_e32 v3, 1.0, v51
	v_pk_mul_f32 v[14:15], v[14:15], v[46:47]
	v_pk_add_f32 v[46:47], v[60:61], v[64:65]
	v_rcp_f32_e32 v51, v3
	v_pk_fma_f32 v[14:15], v[84:85], v[14:15], v[46:47] op_sel_hi:[0,1,1]
	v_lshlrev_b32_e32 v46, 16, v58
	v_and_b32_e32 v47, 0xffff0000, v58
	v_lshlrev_b32_e32 v58, 16, v2
	v_and_b32_e32 v59, 0xffff0000, v2
	v_pk_fma_f32 v[2:3], v[12:13], v[92:93], v[16:17]
	v_lshlrev_b32_e32 v18, 16, v35
	v_pk_fma_f32 v[2:3], v[44:45], v[96:97], v[2:3]
	v_mul_f32_e32 v35, 0xbfb8aa3b, v18
	v_pk_fma_f32 v[2:3], v[48:49], v[58:59], v[2:3]
	v_exp_f32_e32 v35, v35
	v_mul_f32_e32 v12, 0xbfb8aa3b, v2
	v_exp_f32_e32 v16, v12
	v_lshlrev_b32_e32 v12, 16, v34
	v_mul_f32_e32 v17, 0xbfb8aa3b, v12
	v_exp_f32_e32 v17, v17
	v_add_f32_e32 v35, 1.0, v35
	v_and_b32_e32 v13, 0xffff0000, v34
	v_rcp_f32_e32 v50, v35
	v_mul_f32_e32 v34, 0xbfb8aa3b, v3
	v_add_f32_e32 v35, 1.0, v17
	v_mul_f32_e32 v17, 0xbfb8aa3b, v13
	v_exp_f32_e32 v34, v34
	v_exp_f32_e32 v44, v17
	v_pk_fma_f32 v[22:23], v[22:23], v[88:89], v[30:31]
	v_and_b32_e32 v45, 0xffff0000, v1
	v_add_f32_e32 v17, 1.0, v34
	v_rcp_f32_e32 v34, v35
	v_add_f32_e32 v35, 1.0, v44
	v_lshlrev_b32_e32 v44, 16, v1
	v_pk_fma_f32 v[22:23], v[38:39], v[108:109], v[22:23]
	v_add_f32_e32 v16, 1.0, v16
	v_pk_fma_f32 v[22:23], v[42:43], v[44:45], v[22:23]
	v_and_b32_e32 v31, 0xffff0000, v33
	v_mul_f32_e32 v1, 0xbfb8aa3b, v22
	v_exp_f32_e32 v1, v1
	v_rcp_f32_e32 v16, v16
	v_rcp_f32_e32 v17, v17
	v_mul_f32_e32 v39, 0xbfb8aa3b, v31
	v_add_f32_e32 v1, 1.0, v1
	v_rcp_f32_e32 v38, v1
	v_mul_f32_e32 v1, 0xbfb8aa3b, v23
	v_exp_f32_e32 v1, v1
	v_rcp_f32_e32 v35, v35
	v_exp_f32_e32 v43, v39
	v_pk_mul_f32 v[18:19], v[50:51], v[18:19]
	v_lshlrev_b32_e32 v50, 16, v54
	v_and_b32_e32 v51, 0xffff0000, v54
	v_pk_mul_f32 v[2:3], v[2:3], v[16:17]
	v_pk_add_f32 v[16:17], v[46:47], v[50:51]
	v_add_f32_e32 v1, 1.0, v1
	v_pk_fma_f32 v[2:3], v[2:3], v[84:85], v[16:17] op_sel_hi:[1,0,1]
	v_pk_mul_f32 v[12:13], v[34:35], v[12:13]
	v_lshlrev_b32_e32 v16, 16, v57
	v_and_b32_e32 v17, 0xffff0000, v57
	v_lshlrev_b32_e32 v34, 16, v53
	v_and_b32_e32 v35, 0xffff0000, v53
	v_rcp_f32_e32 v39, v1
	v_add_f32_e32 v1, 1.0, v43
	v_rcp_f32_e32 v43, v1
	v_pk_add_f32 v[16:17], v[16:17], v[34:35]
	v_lshlrev_b32_e32 v34, 16, v0
	v_and_b32_e32 v35, 0xffff0000, v0
; DI u32x4 pack8(const float* f) { u32x4 w; w.x = pack2(f[0], f[1]); w.y = pack2(f[2], f[3]); w.z = pack2(f[4], f[5]); w.w = pack2(f[6], f[7]); return w; }
; DI float siluf_(float x) { return x * __builtin_amdgcn_rcpf(1.0f + __expf(-x)); }
; DI void phase_post0(const Ctx& c) {
;     ...
;       for (int j = 0; j < 4; ++j) { const int tj = t0 - 1 + j; R[j] = (tj >= 0 && tj < SEQ) ? ld8(rp + (j - 1) * 2592) : (u32x4){0u, 0u, 0u, 0u}; }
; #pragma unroll
;       for (int i = 0; i < 2; ++i) { Yq[i][0] = ld8(Y0 + (size_t)(tok0 + i) * 1024 + col); Yq[i][1] = ld8(Y1 + (size_t)(tok0 + i) * 1024 + col); Zq[i] = ld8(zp + i * 2592); }
;       float w0[8], w1[8], w2[8], bb[8], nw_[8];
; #pragma unroll
;       for (int j = 0; j < 8; ++j) { w0[j] = cw[col + j]; w1[j] = cw[1536 + col + j]; w2[j] = cw[3072 + col + j]; bb[j] = cb[col + j]; nw_[j] = p.mb_norm_w[col + j]; }
;       const float D = p.mb_D[head];
; #pragma unroll
;       for (int i = 0; i < 2; ++i) {
;         float y0[8], y1[8], z[8], cur[8], prv[8], nxt[8], o[8];
;         unpack8(Yq[i][0], y0); unpack8(Yq[i][1], y1); unpack8(Zq[i], z); unpack8(R[i], prv); unpack8(R[i + 1], cur); unpack8(R[i + 2], nxt);
;         float ss = 0.f;
; #pragma unroll
;         for (int j = 0; j < 8; ++j) { const float xs = siluf_(bb[j] + w0[j] * prv[j] + w1[j] * cur[j] + w2[j] * nxt[j]);
;           const float yy = (y0[j] + y1[j] + D * xs) * siluf_(z[j]); o[j] = yy; ss += yy * yy; }
;         ss = wave_sum(ss);
;         const float rs = rsqrtf(ss * (1.0f / 512.0f) + 1e-5f);
; #pragma unroll
;         for (int j = 0; j < 8; ++j) o[j] = o[j] * rs * nw_[j];
;         *(u32x4*)(zp + i * 2592) = pack8(o);
	v_pk_fma_f32 v[0:1], v[20:21], v[86:87], v[28:29]
	v_lshlrev_b32_e32 v30, 16, v33
	v_pk_fma_f32 v[0:1], v[36:37], v[106:107], v[0:1]
	v_mul_f32_e32 v33, 0xbfb8aa3b, v30
	v_pk_fma_f32 v[0:1], v[40:41], v[34:35], v[0:1]
	v_exp_f32_e32 v33, v33
	v_mul_f32_e32 v20, 0xbfb8aa3b, v0
	v_exp_f32_e32 v28, v20
	v_lshlrev_b32_e32 v20, 16, v32
	v_mul_f32_e32 v29, 0xbfb8aa3b, v20
	v_exp_f32_e32 v29, v29
	v_add_f32_e32 v33, 1.0, v33
	v_and_b32_e32 v21, 0xffff0000, v32
	v_mul_f32_e32 v32, 0xbfb8aa3b, v1
	v_rcp_f32_e32 v42, v33
	v_exp_f32_e32 v32, v32
	v_add_f32_e32 v33, 1.0, v29
	v_mul_f32_e32 v29, 0xbfb8aa3b, v21
	v_exp_f32_e32 v34, v29
	v_add_f32_e32 v28, 1.0, v28
	v_add_f32_e32 v29, 1.0, v32
	v_rcp_f32_e32 v28, v28
	v_rcp_f32_e32 v29, v29
	v_rcp_f32_e32 v32, v33
	v_add_f32_e32 v33, 1.0, v34
	v_pk_mul_f32 v[22:23], v[22:23], v[38:39]
	v_rcp_f32_e32 v33, v33
	v_pk_fma_f32 v[16:17], v[22:23], v[84:85], v[16:17] op_sel_hi:[1,0,1]
	v_pk_mul_f32 v[22:23], v[42:43], v[30:31]
	v_lshlrev_b32_e32 v30, 16, v52
	v_pk_mul_f32 v[16:17], v[22:23], v[16:17]
	v_lshlrev_b32_e32 v22, 16, v56
	v_and_b32_e32 v23, 0xffff0000, v56
	v_and_b32_e32 v31, 0xffff0000, v52
	v_pk_mul_f32 v[0:1], v[0:1], v[28:29]
	v_pk_add_f32 v[22:23], v[22:23], v[30:31]
	v_pk_mul_f32 v[20:21], v[32:33], v[20:21]
	v_pk_fma_f32 v[0:1], v[0:1], v[84:85], v[22:23] op_sel_hi:[1,0,1]
	v_mov_b32_e32 v31, v25
	v_pk_mul_f32 v[20:21], v[20:21], v[0:1]
	v_mov_b32_e32 v29, v24
	v_mov_b32_e32 v30, v21
	v_mov_b32_e32 v28, v20
	v_pk_mul_f32 v[30:31], v[30:31], v[30:31]
	v_pk_mul_f32 v[26:27], v[62:63], v[26:27]
	v_pk_mul_f32 v[12:13], v[12:13], v[2:3]
	v_mov_b32_e32 v0, v16
	v_mov_b32_e32 v1, v66
	v_pk_fma_f32 v[28:29], v[28:29], v[28:29], v[30:31]
	v_pk_mul_f32 v[62:63], v[26:27], v[26:27]
	v_pk_mul_f32 v[2:3], v[12:13], v[12:13]
	v_mov_b32_e32 v22, v17
	v_mov_b32_e32 v23, v67
	v_pk_fma_f32 v[0:1], v[0:1], v[0:1], v[28:29]
	v_pk_mul_f32 v[70:71], v[90:91], v[70:71]
	v_pk_mul_f32 v[14:15], v[18:19], v[14:15]
	v_pk_fma_f32 v[0:1], v[22:23], v[22:23], v[0:1]
	v_mov_b32_e32 v22, v2
	v_mov_b32_e32 v23, v62
	v_pk_mul_f32 v[90:91], v[70:71], v[70:71]
	v_pk_mul_f32 v[18:19], v[14:15], v[14:15]
	v_pk_add_f32 v[0:1], v[22:23], v[0:1]
	v_mov_b32_e32 v62, v3
	v_pk_add_f32 v[0:1], v[62:63], v[0:1]
	v_mov_b32_e32 v2, v18
	v_mov_b32_e32 v3, v90
	v_pk_add_f32 v[0:1], v[2:3], v[0:1]
	v_mov_b32_e32 v90, v19
	v_pk_add_f32 v[0:1], v[90:91], v[0:1]
	s_nop 1
	v_mov_b32_dpp v3, v1 quad_perm:[1,0,3,2] row_mask:0xf bank_mask:0xf bound_ctrl:1
	v_mov_b32_dpp v2, v0 quad_perm:[1,0,3,2] row_mask:0xf bank_mask:0xf bound_ctrl:1
	v_pk_add_f32 v[0:1], v[0:1], v[2:3]
	s_nop 1
	v_mov_b32_dpp v3, v1 quad_perm:[2,3,0,1] row_mask:0xf bank_mask:0xf bound_ctrl:1
	v_mov_b32_dpp v2, v0 quad_perm:[2,3,0,1] row_mask:0xf bank_mask:0xf bound_ctrl:1
	v_pk_add_f32 v[0:1], v[0:1], v[2:3]
	s_nop 1
	v_mov_b32_dpp v3, v1 row_half_mirror row_mask:0xf bank_mask:0xf bound_ctrl:1
	v_mov_b32_dpp v2, v0 row_half_mirror row_mask:0xf bank_mask:0xf bound_ctrl:1
	v_pk_add_f32 v[0:1], v[0:1], v[2:3]
	s_nop 1
	v_mov_b32_dpp v3, v1 row_mirror row_mask:0xf bank_mask:0xf bound_ctrl:1
	v_mov_b32_dpp v2, v0 row_mirror row_mask:0xf bank_mask:0xf bound_ctrl:1
	v_pk_add_f32 v[0:1], v[0:1], v[2:3]
	ds_bpermute_b32 v3, v77, v1
	ds_bpermute_b32 v2, v77, v0
	s_waitcnt lgkmcnt(0)
	v_pk_add_f32 v[0:1], v[0:1], v[2:3]
	ds_bpermute_b32 v3, v85, v1
	ds_bpermute_b32 v2, v85, v0
	s_waitcnt lgkmcnt(0)
	v_pk_add_f32 v[0:1], v[0:1], v[2:3]
	s_nop 0
	v_pk_fma_f32 v[2:3], v[0:1], s[10:11], v[76:77] op_sel_hi:[1,0,0]
	s_nop 0
	v_mul_f32_e32 v0, 0x4b800000, v3
	v_cmp_gt_f32_e32 vcc, s22, v3
	s_nop 1
	v_cndmask_b32_e32 v0, v3, v0, vcc
	v_rsq_f32_e32 v0, v0
	v_mul_f32_e32 v3, 0x4b800000, v2
	v_mul_f32_e32 v1, 0x45800000, v0
	v_cndmask_b32_e32 v0, v0, v1, vcc
	v_pk_mul_f32 v[18:19], v[24:25], v[0:1] op_sel_hi:[1,0]
	v_cmp_gt_f32_e32 vcc, s22, v2
	v_pk_mul_f32 v[18:19], v[8:9], v[18:19]
	v_pk_mul_f32 v[22:23], v[66:67], v[0:1] op_sel_hi:[1,0]
	v_pk_mul_f32 v[24:25], v[26:27], v[0:1] op_sel_hi:[1,0]
	v_pk_mul_f32 v[0:1], v[70:71], v[0:1] op_sel_hi:[1,0]
	v_cndmask_b32_e32 v2, v2, v3, vcc
	v_pk_mul_f32 v[26:27], v[6:7], v[0:1]
	v_cvt_pk_bf16_f32 v0, v18, v19
	v_rsq_f32_e32 v18, v2
	v_pk_mul_f32 v[22:23], v[10:11], v[22:23]
	v_pk_mul_f32 v[24:25], v[4:5], v[24:25]
	v_cvt_pk_bf16_f32 v1, v22, v23
	v_cvt_pk_bf16_f32 v2, v24, v25
	v_cvt_pk_bf16_f32 v3, v26, v27
	global_store_dwordx4 v[78:79], v[0:3], off
	s_nop 1
	v_mul_f32_e32 v0, 0x45800000, v18
	v_cndmask_b32_e32 v0, v18, v0, vcc
	v_pk_mul_f32 v[2:3], v[20:21], v[0:1] op_sel_hi:[1,0]
	v_cmp_lt_i32_e32 vcc, s23, v102
	v_pk_mul_f32 v[2:3], v[8:9], v[2:3]
	v_pk_mul_f32 v[8:9], v[16:17], v[0:1] op_sel_hi:[1,0]
	s_or_b64 s[4:5], vcc, s[4:5]
	v_pk_mul_f32 v[8:9], v[10:11], v[8:9]
	v_pk_mul_f32 v[10:11], v[12:13], v[0:1] op_sel_hi:[1,0]
	v_pk_mul_f32 v[0:1], v[14:15], v[0:1] op_sel_hi:[1,0]
	v_pk_mul_f32 v[4:5], v[4:5], v[10:11]
	v_pk_mul_f32 v[6:7], v[6:7], v[0:1]
	v_cvt_pk_bf16_f32 v0, v2, v3
	v_cvt_pk_bf16_f32 v1, v8, v9
	v_cvt_pk_bf16_f32 v2, v4, v5
	v_cvt_pk_bf16_f32 v3, v6, v7
	global_store_dwordx4 v[82:83], v[0:3], off offset:1088
	s_andn2_b64 exec, exec, s[4:5]
	s_cbranch_execz .LBB0_841
.LBB0_837:
	v_and_or_b32 v22, v103, s17, v80
	v_and_b32_e32 v20, -2, v102
	v_and_b32_e32 v0, 0x7fe, v102
	v_mad_i64_i32 v[2:3], s[12:13], v20, s19, v[72:73]
	v_lshlrev_b32_e32 v74, 1, v22
	v_lshl_add_u64 v[78:79], v[2:3], 0, v[74:75]
	v_cmp_ne_u32_e32 vcc, 0, v0
	v_mov_b32_e32 v4, 0
	v_mov_b32_e32 v5, 0
	v_mov_b32_e32 v6, 0
	v_mov_b32_e32 v7, 0
	s_and_saveexec_b64 s[12:13], vcc
	s_cbranch_execz .LBB0_839
	global_load_dwordx4 v[4:7], v[78:79], off offset:-3136 nt
.LBB0_839:
	s_or_b64 exec, exec, s[12:13]
	v_add_co_u32_e32 v2, vcc, 0x1000, v78
	v_mov_b32_e32 v1, 0
	s_nop 0
	v_addc_co_u32_e32 v3, vcc, 0, v79, vcc
	global_load_dwordx4 v[8:11], v[78:79], off offset:2048 nt
	global_load_dwordx4 v[24:27], v[2:3], off offset:3136 nt
	v_cmp_ne_u32_e32 vcc, s18, v0
	v_mov_b32_e32 v0, 0
	v_mov_b32_e32 v2, 0
	v_mov_b32_e32 v3, 0
	s_and_saveexec_b64 s[12:13], vcc
	s_cbranch_execz .LBB0_836
	v_add_co_u32_e32 v0, vcc, 0x3000, v78
	s_nop 1
	v_addc_co_u32_e32 v1, vcc, 0, v79, vcc
	global_load_dwordx4 v[0:3], v[0:1], off offset:128 nt
	s_branch .LBB0_836

; DI void phase_post1(const Ctx& c) {
;     ...
;     for (int tok0 = gw; tok0 < NTOK; tok0 += 2 * nw) {
;       const int col = lane * 8;
;       u32x4 Q[2][3];
; #pragma unroll
;       for (int i = 0; i < 2; ++i) { const int tok = tok0 + i * nw; if (tok < NTOK) { Q[i][0] = ld8(U + (size_t)tok * 512 + col); Q[i][1] = ld8(Y0 + (size_t)tok * 512 + col); Q[i][2] = ld8(Y1 + (size_t)tok * 512 + col); } }
.LBB0_1729:
	v_ashrrev_i32_e32 v41, 31, v40
	v_lshlrev_b64 v[42:43], 10, v[40:41]
	v_lshl_add_u64 v[28:29], v[32:33], 0, v[42:43]
	v_lshl_add_u64 v[30:31], v[34:35], 0, v[42:43]
	global_load_dwordx4 v[20:23], v[28:29], off nt
	global_load_dwordx4 v[24:27], v[30:31], off nt
	v_lshl_add_u64 v[28:29], v[36:37], 0, v[42:43]
	global_load_dwordx4 v[28:31], v[28:29], off nt
	v_add_u32_e32 v40, s17, v40
	v_cmp_gt_i32_e32 vcc, s8, v40
	v_ashrrev_i32_e32 v41, 31, v40
	s_and_saveexec_b64 s[2:3], vcc
	s_cbranch_execz .LBB0_1731
	v_lshlrev_b64 v[8:9], 10, v[40:41]
	v_lshl_add_u64 v[48:49], v[32:33], 0, v[8:9]
	v_lshl_add_u64 v[50:51], v[34:35], 0, v[8:9]
	v_lshl_add_u64 v[52:53], v[36:37], 0, v[8:9]
	global_load_dwordx4 v[8:11], v[48:49], off nt
	global_load_dwordx4 v[12:15], v[50:51], off nt
	global_load_dwordx4 v[16:19], v[52:53], off nt

; template <int CTRL> DI float dpp_mov(float v) { return __int_as_float(__builtin_amdgcn_update_dpp(0, __float_as_int(v), CTRL, 0xF, 0xF, true)); }
; DI float sum8(float v) { v += dpp_mov<0xB1>(v); v += dpp_mov<0x4E>(v); v += dpp_mov<0x141>(v); return v; }
; DI float sigmoidf_(float x) { return __builtin_amdgcn_rcpf(1.0f + __expf(-x)); }
; DI float siluf_(float x) { return x * __builtin_amdgcn_rcpf(1.0f + __expf(-x)); }
; DI void phase_post1(const Ctx& c) {
;     ...
;       for (int j = 0; j < 4; ++j) { const int tj = t0 - 1 + j; R[j] = (tj >= 0 && tj < SEQ) ? ld8(xp + (j - 1) * 2080) : (u32x4){0u, 0u, 0u, 0u}; }
; #pragma unroll
;       for (int i = 0; i < 2; ++i) { Hq[i][0] = ld8(HF + (size_t)(tok0 + i) * 1024 + cc); Hq[i][1] = ld8(HB + (size_t)(tok0 + i) * 1024 + cc); Oq[i] = ld8(xp + i * 2080 + 1024); }
;       float w0[8], w1[8], w2[8], bb[8], nw_[8], sk[8];
; #pragma unroll
;       for (int j = 0; j < 8; ++j) { w0[j] = p.ml_conv_w[cc + j]; w1[j] = p.ml_conv_w[1024 + cc + j]; w2[j] = p.ml_conv_w[2048 + cc + j]; bb[j] = p.ml_conv_b[cc + j]; nw_[j] = p.ml_norm_w[cc + j]; sk[j] = p.ml_skip[cc + j]; }
; #pragma unroll
;       for (int i = 0; i < 2; ++i) {
;         float hf[8], hb[8], cur[8], prv[8], nxt[8], og[8], o[8];
;         unpack8(Hq[i][0], hf); unpack8(Hq[i][1], hb); unpack8(R[i], prv); unpack8(R[i + 1], cur); unpack8(R[i + 2], nxt); unpack8(Oq[i], og);
;         float sh = 0.f;
; #pragma unroll
;         for (int j = 0; j < 8; ++j) { hf[j] += hb[j]; sh += hf[j]; }
;         sh = sum8(sh); sh += dpp_mov<0x140>(sh);
;         const float mean = sh * (1.0f / 128.0f);
;         float sv = 0.f;
; #pragma unroll
;         for (int j = 0; j < 8; ++j) { hf[j] -= mean; sv += hf[j] * hf[j]; }
;         sv = sum8(sv); sv += dpp_mov<0x140>(sv);
;         const float rs = rsqrtf(sv * (1.0f / 128.0f) + 1e-5f);
; #pragma unroll
;         for (int j = 0; j < 8; ++j) {
;           const float xcv = siluf_(bb[j] + w0[j] * prv[j] + w1[j] * cur[j] + w2[j] * nxt[j]);
;           o[j] = sigmoidf_(og[j]) * (hf[j] * rs * nw_[j]) + sk[j] * xcv;
.LBB0_1797:
	s_or_b64 exec, exec, s[14:15]
	v_ashrrev_i32_e32 v1, 31, v0
	v_lshl_add_u64 v[48:49], s[2:3], 0, v[84:85]
	v_lshlrev_b64 v[0:1], 11, v[0:1]
	v_lshl_add_u64 v[50:51], s[4:5], 0, v[84:85]
	global_load_dwordx4 v[96:99], v[88:89], off offset:2048 nt
	v_lshl_add_u64 v[4:5], v[48:49], 0, v[0:1]
	v_lshl_add_u64 v[0:1], v[50:51], 0, v[0:1]
	global_load_dwordx4 v[76:79], v[4:5], off nt
	global_load_dwordx4 v[72:75], v[0:1], off nt
	v_lshlrev_b32_e32 v84, 2, v2
	v_lshl_add_u64 v[54:55], s[84:85], 0, v[84:85]
	v_lshl_add_u64 v[20:21], v[54:55], 0, s[8:9]
	global_load_dwordx4 v[0:3], v84, s[84:85] offset:16
	global_load_dwordx4 v[4:7], v84, s[86:87] offset:16
	v_lshl_add_u64 v[22:23], v[54:55], 0, s[10:11]
	global_load_dwordx4 v[8:11], v[20:21], off offset:16 nt
	global_load_dwordx4 v[12:15], v[22:23], off offset:16 nt
	global_load_dwordx4 v[36:39], v84, s[84:85]
	global_load_dwordx4 v[40:43], v84, s[86:87]
	v_add_co_u32_e32 v90, vcc, s22, v88
	v_or_b32_e32 v52, 1, v87
	s_nop 0
	v_addc_co_u32_e32 v91, vcc, 0, v89, vcc
	v_ashrrev_i32_e32 v53, 31, v52
	v_readlane_b32 s36, v253, 48
	v_add_co_u32_e32 v100, vcc, s23, v54
	v_readlane_b32 s42, v253, 54
	v_readlane_b32 s43, v253, 55
	v_lshlrev_b64 v[52:53], 11, v[52:53]
	v_addc_co_u32_e32 v101, vcc, 0, v55, vcc
	s_nop 2
	global_load_dwordx4 v[24:27], v84, s[42:43] offset:16
	global_load_dwordx4 v[32:35], v84, s[42:43]
	global_load_dwordx4 v[20:23], v84, s[52:53] offset:16
	global_load_dwordx4 v[28:31], v84, s[52:53]
	v_lshl_add_u64 v[102:103], v[48:49], 0, v[52:53]
	v_lshl_add_u64 v[106:107], v[50:51], 0, v[52:53]
	global_load_dwordx4 v[48:51], v[100:101], off offset:-4096 nt
	global_load_dwordx4 v[52:55], v[100:101], off nt
	global_load_dwordx4 v[68:71], v[102:103], off nt
	global_load_dwordx4 v[64:67], v[106:107], off nt
	global_load_dwordx4 v[110:113], v[90:91], off offset:2112 nt
	s_waitcnt vmcnt(19)
	v_lshlrev_b32_e32 v92, 16, v63
	v_and_b32_e32 v93, 0xffff0000, v63
	v_lshlrev_b32_e32 v104, 16, v47
	v_and_b32_e32 v105, 0xffff0000, v47
	s_waitcnt vmcnt(18)
	v_lshlrev_b32_e32 v94, 16, v59
	v_and_b32_e32 v95, 0xffff0000, v59
	v_lshlrev_b32_e32 v116, 16, v46
	v_and_b32_e32 v117, 0xffff0000, v46
	v_lshlrev_b32_e32 v118, 16, v62
	v_and_b32_e32 v119, 0xffff0000, v62
	v_lshlrev_b32_e32 v120, 16, v58
	v_and_b32_e32 v121, 0xffff0000, v58
	v_lshlrev_b32_e32 v124, 16, v60
	v_and_b32_e32 v125, 0xffff0000, v60
	v_lshlrev_b32_e32 v126, 16, v56
	v_and_b32_e32 v127, 0xffff0000, v56
	v_lshlrev_b32_e32 v132, 16, v19
	v_and_b32_e32 v133, 0xffff0000, v19
	v_add_u32_e32 v108, s18, v108
	v_readlane_b32 s37, v253, 49
	v_readlane_b32 s38, v253, 50
	v_readlane_b32 s39, v253, 51
	v_readlane_b32 s40, v253, 52
	v_readlane_b32 s41, v253, 53
	s_waitcnt vmcnt(17)
	v_lshlrev_b32_e32 v63, 16, v97
	v_and_b32_e32 v84, 0xffff0000, v97
	v_lshlrev_b32_e32 v47, 16, v96
	v_mul_f32_e32 v63, 0xbfb8aa3b, v63
	s_waitcnt vmcnt(15)
	v_lshlrev_b32_e32 v114, 16, v75
	v_and_b32_e32 v115, 0xffff0000, v75
	v_mul_f32_e32 v75, 0xbfb8aa3b, v84
	v_mul_f32_e32 v47, 0xbfb8aa3b, v47
	v_exp_f32_e32 v63, v63
	v_exp_f32_e32 v75, v75
	v_exp_f32_e32 v47, v47
	v_and_b32_e32 v59, 0xffff0000, v96
	v_mul_f32_e32 v59, 0xbfb8aa3b, v59
	v_lshlrev_b32_e32 v106, 16, v79
	v_and_b32_e32 v107, 0xffff0000, v79
	v_exp_f32_e32 v59, v59
	v_add_f32_e32 v63, 1.0, v63
	v_add_f32_e32 v75, 1.0, v75
	v_add_f32_e32 v47, 1.0, v47
	v_rcp_f32_e32 v100, v63
	v_rcp_f32_e32 v101, v75
	v_pk_add_f32 v[106:107], v[106:107], v[114:115]
	v_lshlrev_b32_e32 v114, 16, v78
	v_and_b32_e32 v115, 0xffff0000, v78
	v_lshlrev_b32_e32 v62, 16, v74
	v_and_b32_e32 v63, 0xffff0000, v74
	v_lshlrev_b32_e32 v74, 16, v45
	v_and_b32_e32 v75, 0xffff0000, v45
	v_rcp_f32_e32 v102, v47
	s_waitcnt vmcnt(13)
	v_pk_fma_f32 v[46:47], v[0:1], v[116:117], v[4:5]
	v_pk_add_f32 v[62:63], v[114:115], v[62:63]
	v_lshlrev_b32_e32 v114, 16, v61
	v_and_b32_e32 v115, 0xffff0000, v61
	s_waitcnt vmcnt(9)
	v_pk_fma_f32 v[74:75], v[38:39], v[74:75], v[42:43]
	v_pk_fma_f32 v[46:47], v[8:9], v[118:119], v[46:47]
	v_lshlrev_b32_e32 v116, 16, v57
	v_and_b32_e32 v117, 0xffff0000, v57
	s_waitcnt vmcnt(4)
	v_pk_fma_f32 v[74:75], v[50:51], v[114:115], v[74:75]
	v_add_f32_e32 v59, 1.0, v59
	v_pk_fma_f32 v[46:47], v[12:13], v[120:121], v[46:47]
	s_waitcnt vmcnt(3)
; template <int CTRL> DI float dpp_mov(float v) { return __int_as_float(__builtin_amdgcn_update_dpp(0, __float_as_int(v), CTRL, 0xF, 0xF, true)); }
; DI float sum8(float v) { v += dpp_mov<0xB1>(v); v += dpp_mov<0x4E>(v); v += dpp_mov<0x141>(v); return v; }
; DI float sigmoidf_(float x) { return __builtin_amdgcn_rcpf(1.0f + __expf(-x)); }
; DI float siluf_(float x) { return x * __builtin_amdgcn_rcpf(1.0f + __expf(-x)); }
; DI void phase_post1(const Ctx& c) {
;     ...
;         float hf[8], hb[8], cur[8], prv[8], nxt[8], og[8], o[8];
;         unpack8(Hq[i][0], hf); unpack8(Hq[i][1], hb); unpack8(R[i], prv); unpack8(R[i + 1], cur); unpack8(R[i + 2], nxt); unpack8(Oq[i], og);
;         float sh = 0.f;
; #pragma unroll
;         for (int j = 0; j < 8; ++j) { hf[j] += hb[j]; sh += hf[j]; }
;         sh = sum8(sh); sh += dpp_mov<0x140>(sh);
;         const float mean = sh * (1.0f / 128.0f);
;         float sv = 0.f;
; #pragma unroll
;         for (int j = 0; j < 8; ++j) { hf[j] -= mean; sv += hf[j] * hf[j]; }
;         sv = sum8(sv); sv += dpp_mov<0x140>(sv);
;         const float rs = rsqrtf(sv * (1.0f / 128.0f) + 1e-5f);
; #pragma unroll
;         for (int j = 0; j < 8; ++j) {
;           const float xcv = siluf_(bb[j] + w0[j] * prv[j] + w1[j] * cur[j] + w2[j] * nxt[j]);
;           o[j] = sigmoidf_(og[j]) * (hf[j] * rs * nw_[j]) + sk[j] * xcv;
	v_pk_fma_f32 v[74:75], v[54:55], v[116:117], v[74:75]
	v_lshlrev_b32_e32 v96, 16, v98
	v_rcp_f32_e32 v103, v59
	v_mul_f32_e32 v58, 0xbfb8aa3b, v46
	v_mul_f32_e32 v59, 0xbfb8aa3b, v47
	v_mul_f32_e32 v45, 0xbfb8aa3b, v74
	v_mul_f32_e32 v79, 0xbfb8aa3b, v96
	v_exp_f32_e32 v58, v58
	v_exp_f32_e32 v59, v59
	v_exp_f32_e32 v45, v45
	v_mul_f32_e32 v57, 0xbfb8aa3b, v75
	v_exp_f32_e32 v79, v79
	v_exp_f32_e32 v57, v57
	v_add_f32_e32 v58, 1.0, v58
	v_add_f32_e32 v59, 1.0, v59
	v_add_f32_e32 v45, 1.0, v45
	v_and_b32_e32 v97, 0xffff0000, v98
	v_lshlrev_b32_e32 v98, 16, v99
	v_add_f32_e32 v79, 1.0, v79
	v_rcp_f32_e32 v58, v58
	v_rcp_f32_e32 v59, v59
	v_rcp_f32_e32 v78, v45
	v_add_f32_e32 v45, 1.0, v57
	v_mul_f32_e32 v96, 0xbfb8aa3b, v98
	v_rcp_f32_e32 v98, v79
	v_rcp_f32_e32 v79, v45
	v_pk_mul_f32 v[46:47], v[46:47], v[58:59]
	v_lshlrev_b32_e32 v58, 16, v77
	v_and_b32_e32 v59, 0xffff0000, v77
	v_lshlrev_b32_e32 v122, 16, v73
	v_and_b32_e32 v123, 0xffff0000, v73
	v_pk_add_f32 v[122:123], v[58:59], v[122:123]
	v_pk_mul_f32 v[58:59], v[74:75], v[78:79]
	v_lshlrev_b32_e32 v78, 16, v44
	v_and_b32_e32 v79, 0xffff0000, v44
	v_pk_fma_f32 v[44:45], v[36:37], v[78:79], v[40:41]
	v_lshlrev_b32_e32 v74, 16, v76
	v_pk_fma_f32 v[44:45], v[48:49], v[124:125], v[44:45]
	v_and_b32_e32 v75, 0xffff0000, v76
	v_pk_fma_f32 v[44:45], v[52:53], v[126:127], v[44:45]
	v_lshlrev_b32_e32 v76, 16, v72
	v_mul_f32_e32 v56, 0xbfb8aa3b, v44
	v_mul_f32_e32 v57, 0xbfb8aa3b, v45
	v_exp_f32_e32 v56, v56
	v_exp_f32_e32 v57, v57
	v_and_b32_e32 v77, 0xffff0000, v72
	v_pk_add_f32 v[60:61], v[74:75], v[76:77]
	v_add_f32_e32 v56, 1.0, v56
	v_add_f32_e32 v57, 1.0, v57
	v_rcp_f32_e32 v56, v56
	v_rcp_f32_e32 v57, v57
	v_add_f32_e32 v72, 0, v60
	v_add_f32_e32 v72, v61, v72
	v_pk_fma_f32 v[74:75], v[2:3], v[104:105], v[6:7]
	v_pk_mul_f32 v[44:45], v[44:45], v[56:57]
	v_add_f32_e32 v56, v122, v72
	v_add_f32_e32 v56, v123, v56
	v_add_f32_e32 v56, v62, v56
	v_add_f32_e32 v56, v63, v56
	v_add_f32_e32 v56, v106, v56
	v_add_f32_e32 v56, v107, v56
	v_pk_fma_f32 v[74:75], v[10:11], v[92:93], v[74:75]
	v_mul_f32_e32 v84, 0xbfb8aa3b, v97
	v_add_f32_dpp v56, v56, v56 quad_perm:[1,0,3,2] row_mask:0xf bank_mask:0xf bound_ctrl:1
	v_pk_fma_f32 v[74:75], v[14:15], v[94:95], v[74:75]
	v_exp_f32_e32 v84, v84
	v_add_f32_dpp v56, v56, v56 quad_perm:[2,3,0,1] row_mask:0xf bank_mask:0xf bound_ctrl:1
	v_mul_f32_e32 v76, 0xbfb8aa3b, v75
	v_exp_f32_e32 v78, v76
	v_add_f32_dpp v56, v56, v56 row_half_mirror row_mask:0xf bank_mask:0xf bound_ctrl:1
	v_and_b32_e32 v99, 0xffff0000, v99
	v_add_f32_e32 v84, 1.0, v84
	v_add_f32_dpp v56, v56, v56 row_mirror row_mask:0xf bank_mask:0xf bound_ctrl:1
	v_mul_f32_e32 v72, 0x3c000000, v56
	v_pk_add_f32 v[60:61], v[60:61], v[72:73] op_sel_hi:[1,0] neg_lo:[0,1] neg_hi:[0,1]
	v_pk_add_f32 v[56:57], v[122:123], v[72:73] op_sel_hi:[1,0] neg_lo:[0,1] neg_hi:[0,1]
	v_mul_f32_e32 v73, 0xbfb8aa3b, v74
	v_exp_f32_e32 v73, v73
	v_mul_f32_e32 v97, 0xbfb8aa3b, v99
	v_rcp_f32_e32 v99, v84
	s_waitcnt vmcnt(0)
	v_lshlrev_b32_e32 v84, 16, v112
	v_pk_add_f32 v[76:77], v[62:63], v[72:73] op_sel_hi:[1,0] neg_lo:[0,1] neg_hi:[0,1]
	v_add_f32_e32 v62, 1.0, v73
	v_add_f32_e32 v63, 1.0, v78
	v_rcp_f32_e32 v62, v62
	v_rcp_f32_e32 v63, v63
	v_pk_add_f32 v[78:79], v[106:107], v[72:73] op_sel_hi:[1,0] neg_lo:[0,1] neg_hi:[0,1]
	v_lshlrev_b32_e32 v72, 16, v111
	v_and_b32_e32 v73, 0xffff0000, v111
	v_pk_mul_f32 v[104:105], v[74:75], v[62:63]
	v_lshlrev_b32_e32 v62, 16, v110
	v_and_b32_e32 v63, 0xffff0000, v110
	v_mul_f32_e32 v62, 0xbfb8aa3b, v62
	v_exp_f32_e32 v62, v62
	v_mul_f32_e32 v63, 0xbfb8aa3b, v63
	v_exp_f32_e32 v63, v63
	v_and_b32_e32 v110, 0xffff0000, v113
	v_add_f32_e32 v62, 1.0, v62
	v_and_b32_e32 v107, 0xffff0000, v112
	v_lshlrev_b32_e32 v109, 16, v113
	v_rcp_f32_e32 v74, v62
	v_add_f32_e32 v62, 1.0, v63
	v_mul_f32_e32 v63, 0xbfb8aa3b, v72
	v_mul_f32_e32 v72, 0xbfb8aa3b, v73
	v_mul_f32_e32 v73, 0xbfb8aa3b, v110
	v_lshlrev_b32_e32 v110, 16, v71
	v_and_b32_e32 v111, 0xffff0000, v71
	v_lshlrev_b32_e32 v112, 16, v67
	v_and_b32_e32 v113, 0xffff0000, v67
	v_pk_fma_f32 v[0:1], v[0:1], v[118:119], v[4:5]
	v_pk_add_f32 v[110:111], v[110:111], v[112:113]
	v_lshlrev_b32_e32 v112, 16, v70
	v_and_b32_e32 v113, 0xffff0000, v70
	v_lshlrev_b32_e32 v70, 16, v66
	v_and_b32_e32 v71, 0xffff0000, v66
	v_lshlrev_b32_e32 v66, 16, v18
	v_and_b32_e32 v67, 0xffff0000, v18
	v_pk_fma_f32 v[0:1], v[8:9], v[120:121], v[0:1]
	v_pk_fma_f32 v[38:39], v[38:39], v[114:115], v[42:43]
	v_pk_fma_f32 v[0:1], v[12:13], v[66:67], v[0:1]
	v_lshlrev_b32_e32 v66, 16, v17
	v_and_b32_e32 v67, 0xffff0000, v17
	v_pk_fma_f32 v[38:39], v[50:51], v[116:117], v[38:39]
	v_lshlrev_b32_e32 v12, 16, v69
	v_pk_fma_f32 v[38:39], v[54:55], v[66:67], v[38:39]
	v_and_b32_e32 v13, 0xffff0000, v69
	v_mul_f32_e32 v17, 0xbfb8aa3b, v38
	v_exp_f32_e32 v17, v17
	v_mul_f32_e32 v42, 0xbfb8aa3b, v39
	v_exp_f32_e32 v42, v42
	v_lshlrev_b32_e32 v18, 16, v65
	v_and_b32_e32 v19, 0xffff0000, v65
	v_add_f32_e32 v17, 1.0, v17
	v_pk_add_f32 v[12:13], v[12:13], v[18:19]
	v_rcp_f32_e32 v18, v17
	v_add_f32_e32 v17, 1.0, v42
	v_lshlrev_b32_e32 v42, 16, v68
	v_and_b32_e32 v43, 0xffff0000, v68
	v_lshlrev_b32_e32 v50, 16, v64
	v_and_b32_e32 v51, 0xffff0000, v64
	v_rcp_f32_e32 v19, v17
	v_lshlrev_b32_e32 v54, 16, v16
	v_and_b32_e32 v55, 0xffff0000, v16
	v_pk_add_f32 v[16:17], v[42:43], v[50:51]
	v_mul_f32_e32 v4, 0xbfb8aa3b, v0
	v_add_f32_e32 v42, 0, v16
	v_add_f32_e32 v42, v17, v42
	v_exp_f32_e32 v8, v4
	v_mul_f32_e32 v4, 0xbfb8aa3b, v1
	v_add_f32_e32 v42, v12, v42
	v_exp_f32_e32 v9, v4
	v_pk_add_f32 v[4:5], v[112:113], v[70:71]
	v_add_f32_e32 v42, v13, v42
	v_add_f32_e32 v42, v4, v42
; DI u32x4 pack8(const float* f) { u32x4 w; w.x = pack2(f[0], f[1]); w.y = pack2(f[2], f[3]); w.z = pack2(f[4], f[5]); w.w = pack2(f[6], f[7]); return w; }
; template <int CTRL> DI float dpp_mov(float v) { return __int_as_float(__builtin_amdgcn_update_dpp(0, __float_as_int(v), CTRL, 0xF, 0xF, true)); }
; DI float sum8(float v) { v += dpp_mov<0xB1>(v); v += dpp_mov<0x4E>(v); v += dpp_mov<0x141>(v); return v; }
; DI float sigmoidf_(float x) { return __builtin_amdgcn_rcpf(1.0f + __expf(-x)); }
; DI float siluf_(float x) { return x * __builtin_amdgcn_rcpf(1.0f + __expf(-x)); }
; DI void phase_post1(const Ctx& c) {
;     ...
;         float sv = 0.f;
; #pragma unroll
;         for (int j = 0; j < 8; ++j) { hf[j] -= mean; sv += hf[j] * hf[j]; }
;         sv = sum8(sv); sv += dpp_mov<0x140>(sv);
;         const float rs = rsqrtf(sv * (1.0f / 128.0f) + 1e-5f);
; #pragma unroll
;         for (int j = 0; j < 8; ++j) {
;           const float xcv = siluf_(bb[j] + w0[j] * prv[j] + w1[j] * cur[j] + w2[j] * nxt[j]);
;           o[j] = sigmoidf_(og[j]) * (hf[j] * rs * nw_[j]) + sk[j] * xcv;
;         }
;         *(u32x4*)(xp + i * 2080 + 1024) = pack8(o);
	v_add_f32_e32 v42, v5, v42
	v_add_f32_e32 v42, v110, v42
	v_add_f32_e32 v42, v111, v42
	v_pk_fma_f32 v[36:37], v[36:37], v[124:125], v[40:41]
	v_pk_mul_f32 v[122:123], v[56:57], v[56:57]
	v_add_f32_dpp v42, v42, v42 quad_perm:[1,0,3,2] row_mask:0xf bank_mask:0xf bound_ctrl:1
	v_pk_fma_f32 v[36:37], v[48:49], v[126:127], v[36:37]
	v_mov_b32_e32 v51, v60
	v_add_f32_dpp v42, v42, v42 quad_perm:[2,3,0,1] row_mask:0xf bank_mask:0xf bound_ctrl:1
	v_pk_fma_f32 v[36:37], v[52:53], v[54:55], v[36:37]
	v_mov_b32_e32 v53, v61
	v_add_f32_dpp v42, v42, v42 row_half_mirror row_mask:0xf bank_mask:0xf bound_ctrl:1
	v_pk_mul_f32 v[128:129], v[76:77], v[76:77]
	v_pk_mul_f32 v[130:131], v[78:79], v[78:79]
	v_add_f32_dpp v42, v42, v42 row_mirror row_mask:0xf bank_mask:0xf bound_ctrl:1
	v_mul_f32_e32 v42, 0x3c000000, v42
	v_pk_add_f32 v[48:49], v[16:17], v[42:43] op_sel_hi:[1,0] neg_lo:[0,1] neg_hi:[0,1]
	v_pk_add_f32 v[12:13], v[12:13], v[42:43] op_sel_hi:[1,0] neg_lo:[0,1] neg_hi:[0,1]
	v_mov_b32_e32 v52, v49
	v_pk_mul_f32 v[16:17], v[12:13], v[12:13]
	v_mov_b32_e32 v50, v48
	v_pk_mul_f32 v[52:53], v[52:53], v[52:53]
	v_pk_add_f32 v[4:5], v[4:5], v[42:43] op_sel_hi:[1,0] neg_lo:[0,1] neg_hi:[0,1]
	v_pk_fma_f32 v[50:51], v[50:51], v[50:51], v[52:53]
	v_mov_b32_e32 v52, v16
	v_mov_b32_e32 v53, v122
	v_pk_add_f32 v[50:51], v[52:53], v[50:51]
	v_pk_mul_f32 v[52:53], v[4:5], v[4:5]
	v_mov_b32_e32 v122, v17
	v_pk_add_f32 v[42:43], v[110:111], v[42:43] op_sel_hi:[1,0] neg_lo:[0,1] neg_hi:[0,1]
	v_pk_add_f32 v[16:17], v[122:123], v[50:51]
	v_mov_b32_e32 v50, v52
	v_mov_b32_e32 v51, v128
	v_pk_mul_f32 v[54:55], v[42:43], v[42:43]
	v_pk_add_f32 v[16:17], v[50:51], v[16:17]
	v_mov_b32_e32 v128, v53
	v_pk_add_f32 v[16:17], v[128:129], v[16:17]
	v_mov_b32_e32 v50, v54
	v_mov_b32_e32 v51, v130
	v_pk_add_f32 v[16:17], v[50:51], v[16:17]
	v_mov_b32_e32 v130, v55
	v_pk_add_f32 v[16:17], v[130:131], v[16:17]
	v_mul_f32_e32 v40, 0xbfb8aa3b, v36
	v_mul_f32_e32 v41, 0xbfb8aa3b, v37
	v_mov_b32_dpp v51, v17 quad_perm:[1,0,3,2] row_mask:0xf bank_mask:0xf bound_ctrl:1
	v_mov_b32_dpp v50, v16 quad_perm:[1,0,3,2] row_mask:0xf bank_mask:0xf bound_ctrl:1
	v_pk_add_f32 v[16:17], v[16:17], v[50:51]
	v_exp_f32_e32 v40, v40
	v_exp_f32_e32 v41, v41
	v_mov_b32_dpp v51, v17 quad_perm:[2,3,0,1] row_mask:0xf bank_mask:0xf bound_ctrl:1
	v_mov_b32_dpp v50, v16 quad_perm:[2,3,0,1] row_mask:0xf bank_mask:0xf bound_ctrl:1
	v_pk_add_f32 v[16:17], v[16:17], v[50:51]
	v_exp_f32_e32 v96, v96
	v_exp_f32_e32 v97, v97
	v_mov_b32_dpp v51, v17 row_half_mirror row_mask:0xf bank_mask:0xf bound_ctrl:1
	v_mov_b32_dpp v50, v16 row_half_mirror row_mask:0xf bank_mask:0xf bound_ctrl:1
	v_pk_add_f32 v[16:17], v[16:17], v[50:51]
	v_add_f32_e32 v8, 1.0, v8
	v_add_f32_e32 v9, 1.0, v9
	v_mov_b32_dpp v51, v17 row_mirror row_mask:0xf bank_mask:0xf bound_ctrl:1
	v_mov_b32_dpp v50, v16 row_mirror row_mask:0xf bank_mask:0xf bound_ctrl:1
	v_pk_add_f32 v[16:17], v[16:17], v[50:51]
	v_rcp_f32_e32 v8, v8
	v_pk_fma_f32 v[50:51], v[16:17], s[12:13], v[86:87] op_sel_hi:[1,0,0]
	v_rcp_f32_e32 v9, v9
	v_mul_f32_e32 v16, 0x4b800000, v51
	v_cmp_gt_f32_e32 vcc, s24, v51
	v_add_f32_e32 v40, 1.0, v40
	v_add_f32_e32 v41, 1.0, v41
	v_cndmask_b32_e32 v16, v51, v16, vcc
	v_rsq_f32_e32 v16, v16
	v_exp_f32_e32 v63, v63
	v_rcp_f32_e32 v40, v40
	v_rcp_f32_e32 v41, v41
	v_add_f32_e32 v96, 1.0, v96
	v_add_f32_e32 v97, 1.0, v97
	v_exp_f32_e32 v72, v72
	v_mul_f32_e32 v17, 0x45800000, v16
	v_rcp_f32_e32 v96, v96
	v_rcp_f32_e32 v97, v97
	v_cndmask_b32_e32 v16, v16, v17, vcc
	v_pk_mul_f32 v[0:1], v[0:1], v[8:9]
	v_pk_mul_f32 v[8:9], v[38:39], v[18:19]
	v_pk_mul_f32 v[18:19], v[60:61], v[16:17] op_sel_hi:[1,0]
	v_rcp_f32_e32 v75, v62
	v_add_f32_e32 v62, 1.0, v63
	v_pk_mul_f32 v[36:37], v[36:37], v[40:41]
	v_pk_mul_f32 v[18:19], v[32:33], v[18:19]
	v_pk_mul_f32 v[38:39], v[56:57], v[16:17] op_sel_hi:[1,0]
	v_pk_mul_f32 v[40:41], v[76:77], v[16:17] op_sel_hi:[1,0]
	v_pk_mul_f32 v[16:17], v[78:79], v[16:17] op_sel_hi:[1,0]
	v_rcp_f32_e32 v106, v62
	v_add_f32_e32 v62, 1.0, v72
	v_mul_f32_e32 v63, 0xbfb8aa3b, v84
	v_mul_f32_e32 v72, 0xbfb8aa3b, v107
	v_pk_mul_f32 v[18:19], v[102:103], v[18:19]
	v_pk_mul_f32 v[16:17], v[26:27], v[16:17]
	v_pk_fma_f32 v[2:3], v[2:3], v[92:93], v[6:7]
	v_exp_f32_e32 v63, v63
	v_exp_f32_e32 v72, v72
	v_pk_fma_f32 v[18:19], v[28:29], v[44:45], v[18:19]
	v_pk_mul_f32 v[38:39], v[34:35], v[38:39]
	v_pk_mul_f32 v[16:17], v[96:97], v[16:17]
	v_pk_fma_f32 v[2:3], v[10:11], v[94:95], v[2:3]
	v_pk_mul_f32 v[38:39], v[100:101], v[38:39]
	v_pk_fma_f32 v[44:45], v[22:23], v[104:105], v[16:17]
	v_cvt_pk_bf16_f32 v16, v18, v19
	v_mul_f32_e32 v18, 0x4b800000, v50
	v_cmp_gt_f32_e32 vcc, s24, v50
	v_pk_fma_f32 v[2:3], v[14:15], v[132:133], v[2:3]
	v_pk_fma_f32 v[38:39], v[30:31], v[58:59], v[38:39]
	v_cndmask_b32_e32 v18, v50, v18, vcc
	v_mul_f32_e32 v6, 0xbfb8aa3b, v2
	v_mul_f32_e32 v7, 0xbfb8aa3b, v3
	v_pk_mul_f32 v[40:41], v[24:25], v[40:41]
	v_cvt_pk_bf16_f32 v17, v38, v39
	v_rsq_f32_e32 v38, v18
	v_exp_f32_e32 v6, v6
	v_exp_f32_e32 v7, v7
	v_rcp_f32_e32 v107, v62
	v_add_f32_e32 v62, 1.0, v63
	v_add_f32_e32 v63, 1.0, v72
	v_mul_f32_e32 v72, 0xbfb8aa3b, v109
	v_pk_mul_f32 v[40:41], v[98:99], v[40:41]
	v_exp_f32_e32 v72, v72
	v_exp_f32_e32 v73, v73
	v_pk_fma_f32 v[40:41], v[20:21], v[46:47], v[40:41]
	v_cvt_pk_bf16_f32 v19, v44, v45
	v_cvt_pk_bf16_f32 v18, v40, v41
	v_rcp_f32_e32 v62, v62
	v_rcp_f32_e32 v63, v63
	global_store_dwordx4 v[88:89], v[16:19], off offset:2048
	v_add_f32_e32 v6, 1.0, v6
	v_add_f32_e32 v7, 1.0, v7
	v_mul_f32_e32 v16, 0x45800000, v38
	v_cndmask_b32_e32 v16, v38, v16, vcc
	v_rcp_f32_e32 v6, v6
	v_rcp_f32_e32 v7, v7
	v_add_f32_e32 v72, 1.0, v72
	v_add_f32_e32 v73, 1.0, v73
	v_pk_mul_f32 v[4:5], v[4:5], v[16:17] op_sel_hi:[1,0]
	v_rcp_f32_e32 v72, v72
	v_rcp_f32_e32 v73, v73
	v_pk_mul_f32 v[4:5], v[24:25], v[4:5]
	v_pk_mul_f32 v[18:19], v[48:49], v[16:17] op_sel_hi:[1,0]
	v_pk_mul_f32 v[4:5], v[62:63], v[4:5]
	v_pk_mul_f32 v[12:13], v[12:13], v[16:17] op_sel_hi:[1,0]
	v_pk_fma_f32 v[4:5], v[20:21], v[0:1], v[4:5]
	v_pk_mul_f32 v[0:1], v[2:3], v[6:7]
	v_pk_mul_f32 v[2:3], v[42:43], v[16:17] op_sel_hi:[1,0]
	v_pk_mul_f32 v[18:19], v[32:33], v[18:19]
	v_pk_mul_f32 v[12:13], v[34:35], v[12:13]
	v_pk_mul_f32 v[2:3], v[26:27], v[2:3]
	v_pk_mul_f32 v[18:19], v[74:75], v[18:19]
	v_pk_mul_f32 v[12:13], v[106:107], v[12:13]
	v_pk_mul_f32 v[2:3], v[72:73], v[2:3]
	v_add_u32_e32 v87, s17, v87
	v_pk_fma_f32 v[18:19], v[28:29], v[36:37], v[18:19]
	v_pk_fma_f32 v[8:9], v[30:31], v[8:9], v[12:13]
	v_pk_fma_f32 v[6:7], v[22:23], v[0:1], v[2:3]
	v_cmp_lt_i32_e32 vcc, s25, v87
	v_cvt_pk_bf16_f32 v0, v18, v19
	v_cvt_pk_bf16_f32 v1, v8, v9
	v_cvt_pk_bf16_f32 v2, v4, v5
	v_cvt_pk_bf16_f32 v3, v6, v7
	s_or_b64 s[6:7], vcc, s[6:7]
	global_store_dwordx4 v[90:91], v[0:3], off offset:2112
	s_andn2_b64 exec, exec, s[6:7]
	s_cbranch_execz .LBB0_1802
; DI void phase_post1(const Ctx& c) {
;     ...
;       const int tp = u >> 1, cc = (u & 1) * 512 + lane * 8, tok0 = tp * 2, t0 = tok0 & (SEQ - 1);
;       bf16_t* xp = raw + (size_t)tok0 * 2080 + cc;
;       u32x4 R[4], Hq[2][2], Oq[2];
; #pragma unroll
;       for (int j = 0; j < 4; ++j) { const int tj = t0 - 1 + j; R[j] = (tj >= 0 && tj < SEQ) ? ld8(xp + (j - 1) * 2080) : (u32x4){0u, 0u, 0u, 0u}; }
.LBB0_1798:
	v_and_or_b32 v2, v108, s19, v80
	v_and_b32_e32 v0, -2, v87
	v_and_b32_e32 v1, 0x7fe, v87
	v_mad_i64_i32 v[4:5], s[14:15], v0, s21, v[82:83]
	v_lshlrev_b32_e32 v84, 1, v2
	v_lshl_add_u64 v[88:89], v[4:5], 0, v[84:85]
	v_cmp_ne_u32_e32 vcc, 0, v1
	v_mov_b32_e32 v44, 0
	v_mov_b32_e32 v45, 0
	v_mov_b32_e32 v46, 0
	v_mov_b32_e32 v47, 0
	s_and_saveexec_b64 s[14:15], vcc
	s_cbranch_execz .LBB0_1800
	v_add_co_u32_e32 v4, vcc, 0xfffff000, v88
	s_nop 1
	v_addc_co_u32_e32 v5, vcc, -1, v89, vcc
	global_load_dwordx4 v[44:47], v[4:5], off offset:-64 nt
.LBB0_1800:
	s_or_b64 exec, exec, s[14:15]
	v_add_co_u32_e32 v4, vcc, 0x1000, v88
	v_mov_b32_e32 v16, 0
	s_nop 0
	v_addc_co_u32_e32 v5, vcc, 0, v89, vcc
	global_load_dwordx4 v[60:63], v[88:89], off nt
	global_load_dwordx4 v[56:59], v[4:5], off offset:64 nt
	v_cmp_ne_u32_e32 vcc, s20, v1
	v_mov_b32_e32 v17, 0
	v_mov_b32_e32 v18, 0
	v_mov_b32_e32 v19, 0
	s_and_saveexec_b64 s[14:15], vcc
	s_cbranch_execz .LBB0_1797
	v_add_co_u32_e32 v4, vcc, 0x2000, v88
	s_nop 1
	v_addc_co_u32_e32 v5, vcc, 0, v89, vcc
	global_load_dwordx4 v[16:19], v[4:5], off offset:128 nt
	s_branch .LBB0_1797
